# v9 with K rotation also staggered by N tile (tiles sharing the x rows start 4 K-steps apart)
# baseline (speedup 1.0000x reference)
.LBB0_129:
	s_lshl_b32 s0, s68, 3
	s_and_b32 s16, s0, 56
	s_bfe_u32 s0, s68, 0x30003
	s_or_b32 s24, s16, s0
	s_lshl_b32 s38, s68, 2
	s_lshr_b32 s25, s68, 3
	s_and_b32 s50, s38, 0xffffff00
	s_lshl_b32 s0, s24, 19
	s_add_u32 s4, s41, s0
	s_addc_u32 s5, s49, 0
	s_ashr_i32 s51, s50, 31
	s_lshl_b64 s[0:1], s[50:51], 11
	s_add_u32 s26, s21, s0
	v_readfirstlane_b32 s0, v144
	s_addc_u32 s27, s33, s1
	s_ashr_i32 s28, s0, 6
	s_lshl_b32 s0, s28, 5
	s_ashr_i32 s1, s0, 31
	s_lshl_b64 s[0:1], s[0:1], 11
	s_add_u32 s4, s4, s0
	s_addc_u32 s5, s5, s1
	s_add_u32 s0, s26, s0
	s_addc_u32 s1, s27, s1
	s_lshl_b32 s26, s28, 12
	s_add_i32 s27, s26, 0x8000
	s_and_b32 s81, s24, 7
	s_lshl_b32 s81, s81, 8
	s_and_b32 s82, s50, 0x300
	s_lshl_b32 s82, s82, 1
	s_add_u32 s81, s81, s82
	s_and_b32 s81, s81, 0x7ff
	s_add_u32 s4, s4, s81
	s_addc_u32 s5, s5, 0
	s_add_u32 s0, s0, s81
	s_addc_u32 s1, s1, 0
	s_cmp_eq_u32 s80, 1
	s_cbranch_scc1 .Lpf_skip_L0
	s_add_u32 s28, s4, 0x4000
	s_barrier
	s_mov_b32 m0, s26
	global_load_lds_dwordx4 v145, s[4:5]
	s_addc_u32 s29, s5, 0
	s_or_b32 s30, s26, 0x400
	s_mov_b32 m0, s30
	global_load_lds_dwordx4 v185, s[28:29]
	s_add_u32 s28, s4, 0x8000
	s_addc_u32 s29, s5, 0
	s_or_b32 s30, s26, 0x800
	s_mov_b32 m0, s30
	global_load_lds_dwordx4 v145, s[28:29]
	s_add_u32 s28, s4, 0xc000
	s_addc_u32 s29, s5, 0
	s_or_b32 s30, s26, 0xc00
	s_mov_b32 m0, s30
	global_load_lds_dwordx4 v185, s[28:29]
	s_add_u32 s28, s0, 0x4000
	s_mov_b32 m0, s27
	global_load_lds_dwordx4 v145, s[0:1]
	s_addc_u32 s29, s1, 0
	s_add_i32 s27, s26, 0x8400
	s_mov_b32 m0, s27
	global_load_lds_dwordx4 v185, s[28:29]
	s_add_u32 s28, s0, 0x8000
	s_addc_u32 s29, s1, 0
	s_add_i32 s27, s26, 0x8800
	s_mov_b32 m0, s27
	global_load_lds_dwordx4 v145, s[28:29]
	s_add_u32 s28, s0, 0xc000
	s_addc_u32 s29, s1, 0
	s_add_i32 s27, s26, 0x8c00
	s_mov_b32 m0, s27
	global_load_lds_dwordx4 v185, s[28:29]

.Lpe_notv_L0:
	s_cmp_ge_u32 s25, 9
	s_cbranch_scc1 .Lpe_gates_L0
	s_lshr_b32 s34, s25, 1
	s_cmp_ge_u32 s25, 6
	s_cselect_b32 s35, 1, 0
	s_sub_u32 s34, s34, s35
	s_lshl_b32 s35, s98, 2
	s_add_u32 s35, s35, s34
	s_lshl_b32 s35, s35, 8
	v_readlane_b32 s82, v254, 14
	v_readlane_b32 s83, v254, 15
	s_add_u32 s82, s82, s35
	s_addc_u32 s83, s83, 0
	global_load_dwordx4 v[198:201], v146, s[82:83] offset:0
	global_load_dwordx4 v[202:205], v146, s[82:83] offset:32
	global_load_dwordx4 v[206:209], v146, s[82:83] offset:64
	global_load_dwordx4 v[210:213], v146, s[82:83] offset:96
	global_load_dwordx4 v[214:217], v146, s[82:83] offset:128
	global_load_dwordx4 v[218:221], v146, s[82:83] offset:160
	global_load_dwordx4 v[222:225], v146, s[82:83] offset:192
	global_load_dwordx4 v[226:229], v146, s[82:83] offset:224
	s_and_b32 s35, s34, 1
	s_cmp_eq_u32 s35, 0
	s_cselect_b32 s36, 0x3e000000, 1.0
	s_and_b32 s35, s29, 0x7ff
	s_lshl_b32 s35, s35, 7
	s_add_u32 s96, s72, 0x1ada0000
	s_addc_u32 s97, s73, 0
	s_add_u32 s96, s96, s35
	s_addc_u32 s97, s97, 0
	s_add_u32 s100, s96, 0x40000
	s_addc_u32 s101, s97, 0
	s_cmp_ge_u32 s34, 2
	s_cselect_b32 s37, 1, 0
	s_waitcnt vmcnt(8)
	v_lshlrev_b32_e32 v180, 7, v197
	v_add_u32_e32 v180, v180, v146
	v_mov_b32_e32 v197, 0x358637bd
	v_pk_add_f32 v[128:129], v[128:129], v[130:131]
	v_pk_add_f32 v[132:133], v[132:133], v[134:135]
	v_pk_add_f32 v[136:137], v[136:137], v[138:139]
	v_pk_add_f32 v[140:141], v[140:141], v[142:143]
	v_pk_add_f32 v[164:165], v[164:165], v[166:167]
	v_pk_add_f32 v[168:169], v[168:169], v[170:171]
	v_pk_add_f32 v[246:247], v[246:247], v[248:249]
	v_pk_add_f32 v[250:251], v[250:251], v[252:253]
	v_pk_add_f32 v[128:129], v[128:129], v[132:133]
	v_pk_add_f32 v[136:137], v[136:137], v[140:141]
	v_pk_add_f32 v[164:165], v[164:165], v[168:169]
	v_pk_add_f32 v[246:247], v[246:247], v[250:251]
	v_add_f32_e32 v128, v128, v129
	v_add_f32_e32 v136, v136, v137
	v_add_f32_e32 v164, v164, v165
	v_add_f32_e32 v246, v246, v247
	v_fmamk_f32 v128, v128, 0x3a800000, v197
	v_fmamk_f32 v136, v136, 0x3a800000, v197
	v_fmamk_f32 v164, v164, 0x3a800000, v197
	v_fmamk_f32 v246, v246, 0x3a800000, v197
	v_rsq_f32_e32 v172, v128
	v_rsq_f32_e32 v173, v136
	v_rsq_f32_e32 v174, v164
	v_rsq_f32_e32 v175, v246
	s_nop 0
	s_add_u32 s76, s99, s90
	s_cmp_lt_u32 s76, 0x440
	s_cselect_b32 s80, 1, 0
	s_cselect_b32 s83, 0x200000, 0
	s_lshl_b32 s76, s24, 19
	s_lshl_b32 s77, s26, 16
	s_add_u32 s76, s76, s77
	s_and_b32 s77, s24, 7
	s_lshl_b32 s77, s77, 8
	s_and_b32 s82, s25, 3
	s_lshl_b32 s82, s82, 9
	s_add_u32 s77, s77, s82
	s_and_b32 s77, s77, 0x7ff
	s_add_u32 s76, s76, s77
	s_add_u32 s78, s72, 0xa120000
	s_addc_u32 s79, s73, 0
	s_add_u32 s78, s78, s76
	s_addc_u32 s79, s79, 0
	s_lshl_b32 s76, s25, 19
	s_add_u32 s76, s76, s83
	s_add_u32 s76, s76, s77
	s_lshl_b32 s77, s26, 16
	s_add_u32 s76, s76, s77
	s_add_u32 s82, s72, 0x0
	s_addc_u32 s83, s73, 0
	s_add_u32 s82, s82, s76
	s_addc_u32 s83, s83, 0
	s_lshl_b32 s76, s26, 12
	s_mov_b32 m0, s76
	s_nop 0
	global_load_lds_dwordx4 v145, s[78:79]
	s_add_u32 s78, s78, 0x4000
	s_addc_u32 s79, s79, 0
	s_add_u32 s76, s76, 0x400
	s_mov_b32 m0, s76
	s_nop 0
	global_load_lds_dwordx4 v185, s[78:79]
	s_add_u32 s78, s78, 0x4000
	s_addc_u32 s79, s79, 0
	s_add_u32 s76, s76, 0x400
	s_mov_b32 m0, s76
	s_nop 0
	global_load_lds_dwordx4 v145, s[78:79]
	s_add_u32 s78, s78, 0x4000
	s_addc_u32 s79, s79, 0
	s_add_u32 s76, s76, 0x400
	s_mov_b32 m0, s76
	s_nop 0
	global_load_lds_dwordx4 v185, s[78:79]
	s_add_u32 s78, s78, 0x4000
	s_addc_u32 s79, s79, 0
	s_add_u32 s76, s76, 0x400
	s_add_u32 s76, s76, 0x7000
	s_mov_b32 m0, s76
	s_nop 0
	global_load_lds_dwordx4 v145, s[82:83]
	s_add_u32 s82, s82, 0x4000
	s_addc_u32 s83, s83, 0
	s_add_u32 s76, s76, 0x400
	s_mov_b32 m0, s76
	s_nop 0
	global_load_lds_dwordx4 v185, s[82:83]
	s_add_u32 s82, s82, 0x4000
	s_addc_u32 s83, s83, 0
	s_add_u32 s76, s76, 0x400
	s_mov_b32 m0, s76
	s_nop 0
	global_load_lds_dwordx4 v145, s[82:83]
	s_add_u32 s82, s82, 0x4000
	s_addc_u32 s83, s83, 0
	s_add_u32 s76, s76, 0x400
	s_mov_b32 m0, s76
	s_nop 0
	global_load_lds_dwordx4 v185, s[82:83]
	s_add_u32 s82, s82, 0x4000
	s_addc_u32 s83, s83, 0
	s_add_u32 s76, s76, 0x400
	s_cmp_eq_u32 s37, 0
	s_cbranch_scc1 .Lpe_norope_ld_L0
	global_load_dwordx4 v[230:233], v180, s[96:97] offset:0
	global_load_dwordx4 v[234:237], v180, s[96:97] offset:32
	global_load_dwordx4 v[238:241], v180, s[96:97] offset:64
	global_load_dwordx4 v[242:245], v180, s[96:97] offset:96
	global_load_dwordx4 v[148:151], v180, s[100:101] offset:0
	global_load_dwordx4 v[152:155], v180, s[100:101] offset:32
	global_load_dwordx4 v[156:159], v180, s[100:101] offset:64
	global_load_dwordx4 v[160:163], v180, s[100:101] offset:96

.Lpe_gates_L0:
	s_lshl_b32 s35, s98, 11
	s_add_u32 s35, s35, s30
	s_sub_u32 s35, s35, 0x900
	s_lshl_b32 s35, s35, 2
	v_readlane_b32 s82, v254, 12
	v_readlane_b32 s83, v254, 13
	s_add_u32 s82, s82, s35
	s_addc_u32 s83, s83, 0
	global_load_dwordx4 v[198:201], v146, s[82:83] offset:0
	global_load_dwordx4 v[202:205], v146, s[82:83] offset:32
	global_load_dwordx4 v[206:209], v146, s[82:83] offset:64
	global_load_dwordx4 v[210:213], v146, s[82:83] offset:96
	global_load_dwordx4 v[214:217], v146, s[82:83] offset:128
	global_load_dwordx4 v[218:221], v146, s[82:83] offset:160
	global_load_dwordx4 v[222:225], v146, s[82:83] offset:192
	global_load_dwordx4 v[226:229], v146, s[82:83] offset:224
	s_waitcnt vmcnt(8)
	v_mov_b32_e32 v197, 0x358637bd
	v_pk_add_f32 v[128:129], v[128:129], v[130:131]
	v_pk_add_f32 v[132:133], v[132:133], v[134:135]
	v_pk_add_f32 v[136:137], v[136:137], v[138:139]
	v_pk_add_f32 v[140:141], v[140:141], v[142:143]
	v_pk_add_f32 v[164:165], v[164:165], v[166:167]
	v_pk_add_f32 v[168:169], v[168:169], v[170:171]
	v_pk_add_f32 v[246:247], v[246:247], v[248:249]
	v_pk_add_f32 v[250:251], v[250:251], v[252:253]
	v_pk_add_f32 v[128:129], v[128:129], v[132:133]
	v_pk_add_f32 v[136:137], v[136:137], v[140:141]
	v_pk_add_f32 v[164:165], v[164:165], v[168:169]
	v_pk_add_f32 v[246:247], v[246:247], v[250:251]
	v_add_f32_e32 v128, v128, v129
	v_add_f32_e32 v136, v136, v137
	v_add_f32_e32 v164, v164, v165
	v_add_f32_e32 v246, v246, v247
	v_fmamk_f32 v128, v128, 0x3a800000, v197
	v_fmamk_f32 v136, v136, 0x3a800000, v197
	v_fmamk_f32 v164, v164, 0x3a800000, v197
	v_fmamk_f32 v246, v246, 0x3a800000, v197
	v_rsq_f32_e32 v172, v128
	v_rsq_f32_e32 v173, v136
	v_rsq_f32_e32 v174, v164
	v_rsq_f32_e32 v175, v246
	s_nop 0
	s_add_u32 s76, s99, s90
	s_cmp_lt_u32 s76, 0x440
	s_cselect_b32 s80, 1, 0
	s_cselect_b32 s83, 0x200000, 0
	s_lshl_b32 s76, s24, 19
	s_lshl_b32 s77, s26, 16
	s_add_u32 s76, s76, s77
	s_and_b32 s77, s24, 7
	s_lshl_b32 s77, s77, 8
	s_and_b32 s82, s25, 3
	s_lshl_b32 s82, s82, 9
	s_add_u32 s77, s77, s82
	s_and_b32 s77, s77, 0x7ff
	s_add_u32 s76, s76, s77
	s_add_u32 s78, s72, 0xa120000
	s_addc_u32 s79, s73, 0
	s_add_u32 s78, s78, s76
	s_addc_u32 s79, s79, 0
	s_lshl_b32 s76, s25, 19
	s_add_u32 s76, s76, s83
	s_add_u32 s76, s76, s77
	s_lshl_b32 s77, s26, 16
	s_add_u32 s76, s76, s77
	s_add_u32 s82, s72, 0x0
	s_addc_u32 s83, s73, 0
	s_add_u32 s82, s82, s76
	s_addc_u32 s83, s83, 0
	s_lshl_b32 s76, s26, 12
	s_mov_b32 m0, s76
	s_nop 0
	global_load_lds_dwordx4 v145, s[78:79]
	s_add_u32 s78, s78, 0x4000
	s_addc_u32 s79, s79, 0
	s_add_u32 s76, s76, 0x400
	s_mov_b32 m0, s76
	s_nop 0
	global_load_lds_dwordx4 v185, s[78:79]
	s_add_u32 s78, s78, 0x4000
	s_addc_u32 s79, s79, 0
	s_add_u32 s76, s76, 0x400
	s_mov_b32 m0, s76
	s_nop 0
	global_load_lds_dwordx4 v145, s[78:79]
	s_add_u32 s78, s78, 0x4000
	s_addc_u32 s79, s79, 0
	s_add_u32 s76, s76, 0x400
	s_mov_b32 m0, s76
	s_nop 0
	global_load_lds_dwordx4 v185, s[78:79]
	s_add_u32 s78, s78, 0x4000
	s_addc_u32 s79, s79, 0
	s_add_u32 s76, s76, 0x400
	s_add_u32 s76, s76, 0x7000
	s_mov_b32 m0, s76
	s_nop 0
	global_load_lds_dwordx4 v145, s[82:83]
	s_add_u32 s82, s82, 0x4000
	s_addc_u32 s83, s83, 0
	s_add_u32 s76, s76, 0x400
	s_mov_b32 m0, s76
	s_nop 0
	global_load_lds_dwordx4 v185, s[82:83]
	s_add_u32 s82, s82, 0x4000
	s_addc_u32 s83, s83, 0
	s_add_u32 s76, s76, 0x400
	s_mov_b32 m0, s76
	s_nop 0
	global_load_lds_dwordx4 v145, s[82:83]
	s_add_u32 s82, s82, 0x4000
	s_addc_u32 s83, s83, 0
	s_add_u32 s76, s76, 0x400
	s_mov_b32 m0, s76
	s_nop 0
	global_load_lds_dwordx4 v185, s[82:83]
	s_add_u32 s82, s82, 0x4000
	s_addc_u32 s83, s83, 0
	s_add_u32 s76, s76, 0x400
	v_mul_f32_e32 v172, 0xbfb8aa3b, v172
	v_mul_f32_e32 v173, 0xbfb8aa3b, v173
	v_mul_f32_e32 v174, 0xbfb8aa3b, v174
	v_mul_f32_e32 v175, 0xbfb8aa3b, v175
	s_waitcnt vmcnt(8)
	v_mul_f32_e32 v198, 0xbfb8aa3b, v198
	v_mul_f32_e32 v199, 0xbfb8aa3b, v199
	v_mul_f32_e32 v200, 0xbfb8aa3b, v200
	v_mul_f32_e32 v201, 0xbfb8aa3b, v201
	v_mul_f32_e32 v202, 0xbfb8aa3b, v202
	v_mul_f32_e32 v203, 0xbfb8aa3b, v203
	v_mul_f32_e32 v204, 0xbfb8aa3b, v204
	v_mul_f32_e32 v205, 0xbfb8aa3b, v205
	v_mul_f32_e32 v206, 0xbfb8aa3b, v206
	v_mul_f32_e32 v207, 0xbfb8aa3b, v207
	v_mul_f32_e32 v208, 0xbfb8aa3b, v208
	v_mul_f32_e32 v209, 0xbfb8aa3b, v209
	v_mul_f32_e32 v210, 0xbfb8aa3b, v210
	v_mul_f32_e32 v211, 0xbfb8aa3b, v211
	v_mul_f32_e32 v212, 0xbfb8aa3b, v212
	v_mul_f32_e32 v213, 0xbfb8aa3b, v213
	v_mul_f32_e32 v214, 0xbfb8aa3b, v214
	v_mul_f32_e32 v215, 0xbfb8aa3b, v215
	v_mul_f32_e32 v216, 0xbfb8aa3b, v216
	v_mul_f32_e32 v217, 0xbfb8aa3b, v217
	v_mul_f32_e32 v218, 0xbfb8aa3b, v218
	v_mul_f32_e32 v219, 0xbfb8aa3b, v219
	v_mul_f32_e32 v220, 0xbfb8aa3b, v220
	v_mul_f32_e32 v221, 0xbfb8aa3b, v221
	v_mul_f32_e32 v222, 0xbfb8aa3b, v222
	v_mul_f32_e32 v223, 0xbfb8aa3b, v223
	v_mul_f32_e32 v224, 0xbfb8aa3b, v224
	v_mul_f32_e32 v225, 0xbfb8aa3b, v225
	v_mul_f32_e32 v226, 0xbfb8aa3b, v226
	v_mul_f32_e32 v227, 0xbfb8aa3b, v227
	v_mul_f32_e32 v228, 0xbfb8aa3b, v228
	v_mul_f32_e32 v229, 0xbfb8aa3b, v229
	v_pk_fma_f32 v[0:1], v[0:1], v[172:173], v[198:199] op_sel_hi:[1,0,1]
	v_pk_fma_f32 v[2:3], v[2:3], v[172:173], v[200:201] op_sel_hi:[1,0,1]
	v_pk_fma_f32 v[4:5], v[4:5], v[172:173], v[202:203] op_sel_hi:[1,0,1]
	v_pk_fma_f32 v[6:7], v[6:7], v[172:173], v[204:205] op_sel_hi:[1,0,1]
	v_pk_fma_f32 v[8:9], v[8:9], v[172:173], v[206:207] op_sel_hi:[1,0,1]
	v_pk_fma_f32 v[10:11], v[10:11], v[172:173], v[208:209] op_sel_hi:[1,0,1]
	v_pk_fma_f32 v[12:13], v[12:13], v[172:173], v[210:211] op_sel_hi:[1,0,1]
	v_pk_fma_f32 v[14:15], v[14:15], v[172:173], v[212:213] op_sel_hi:[1,0,1]
	v_pk_fma_f32 v[16:17], v[16:17], v[172:173], v[214:215] op_sel_hi:[1,0,1]
	v_pk_fma_f32 v[18:19], v[18:19], v[172:173], v[216:217] op_sel_hi:[1,0,1]
	v_pk_fma_f32 v[20:21], v[20:21], v[172:173], v[218:219] op_sel_hi:[1,0,1]
	v_pk_fma_f32 v[22:23], v[22:23], v[172:173], v[220:221] op_sel_hi:[1,0,1]
	v_pk_fma_f32 v[24:25], v[24:25], v[172:173], v[222:223] op_sel_hi:[1,0,1]
	v_pk_fma_f32 v[26:27], v[26:27], v[172:173], v[224:225] op_sel_hi:[1,0,1]
	v_pk_fma_f32 v[28:29], v[28:29], v[172:173], v[226:227] op_sel_hi:[1,0,1]
	v_pk_fma_f32 v[30:31], v[30:31], v[172:173], v[228:229] op_sel_hi:[1,0,1]
	v_exp_f32_e32 v0, v0
	v_exp_f32_e32 v1, v1
	v_exp_f32_e32 v2, v2
	v_exp_f32_e32 v3, v3
	v_exp_f32_e32 v4, v4
	v_exp_f32_e32 v5, v5
	v_exp_f32_e32 v6, v6
	v_exp_f32_e32 v7, v7
	v_exp_f32_e32 v8, v8
	v_exp_f32_e32 v9, v9
	v_exp_f32_e32 v10, v10
	v_exp_f32_e32 v11, v11
	v_exp_f32_e32 v12, v12
	v_exp_f32_e32 v13, v13
	v_exp_f32_e32 v14, v14
	v_exp_f32_e32 v15, v15
	v_exp_f32_e32 v16, v16
	v_exp_f32_e32 v17, v17
	v_exp_f32_e32 v18, v18
	v_exp_f32_e32 v19, v19
	v_exp_f32_e32 v20, v20
	v_exp_f32_e32 v21, v21
	v_exp_f32_e32 v22, v22
	v_exp_f32_e32 v23, v23
	v_exp_f32_e32 v24, v24
	v_exp_f32_e32 v25, v25
	v_exp_f32_e32 v26, v26
	v_exp_f32_e32 v27, v27
	v_exp_f32_e32 v28, v28
	v_exp_f32_e32 v29, v29
	v_exp_f32_e32 v30, v30
	v_exp_f32_e32 v31, v31
	v_pk_add_f32 v[0:1], v[0:1], 1.0 op_sel_hi:[1,0]
	v_pk_add_f32 v[2:3], v[2:3], 1.0 op_sel_hi:[1,0]
	v_pk_add_f32 v[4:5], v[4:5], 1.0 op_sel_hi:[1,0]
	v_pk_add_f32 v[6:7], v[6:7], 1.0 op_sel_hi:[1,0]
	v_pk_add_f32 v[8:9], v[8:9], 1.0 op_sel_hi:[1,0]
	v_pk_add_f32 v[10:11], v[10:11], 1.0 op_sel_hi:[1,0]
	v_pk_add_f32 v[12:13], v[12:13], 1.0 op_sel_hi:[1,0]
	v_pk_add_f32 v[14:15], v[14:15], 1.0 op_sel_hi:[1,0]
	v_pk_add_f32 v[16:17], v[16:17], 1.0 op_sel_hi:[1,0]
	v_pk_add_f32 v[18:19], v[18:19], 1.0 op_sel_hi:[1,0]
	v_pk_add_f32 v[20:21], v[20:21], 1.0 op_sel_hi:[1,0]
	v_pk_add_f32 v[22:23], v[22:23], 1.0 op_sel_hi:[1,0]
	v_pk_add_f32 v[24:25], v[24:25], 1.0 op_sel_hi:[1,0]
	v_pk_add_f32 v[26:27], v[26:27], 1.0 op_sel_hi:[1,0]
	v_pk_add_f32 v[28:29], v[28:29], 1.0 op_sel_hi:[1,0]
	v_pk_add_f32 v[30:31], v[30:31], 1.0 op_sel_hi:[1,0]
	v_rcp_f32_e32 v0, v0
	v_rcp_f32_e32 v1, v1
	v_rcp_f32_e32 v2, v2
	v_rcp_f32_e32 v3, v3
	v_rcp_f32_e32 v4, v4
	v_rcp_f32_e32 v5, v5
	v_rcp_f32_e32 v6, v6
	v_rcp_f32_e32 v7, v7
	v_rcp_f32_e32 v8, v8
	v_rcp_f32_e32 v9, v9
	v_rcp_f32_e32 v10, v10
	v_rcp_f32_e32 v11, v11
	v_rcp_f32_e32 v12, v12
	v_rcp_f32_e32 v13, v13
	v_rcp_f32_e32 v14, v14
	v_rcp_f32_e32 v15, v15
	v_rcp_f32_e32 v16, v16
	v_rcp_f32_e32 v17, v17
	v_rcp_f32_e32 v18, v18
	v_rcp_f32_e32 v19, v19
	v_rcp_f32_e32 v20, v20
	v_rcp_f32_e32 v21, v21
	v_rcp_f32_e32 v22, v22
	v_rcp_f32_e32 v23, v23
	v_rcp_f32_e32 v24, v24
	v_rcp_f32_e32 v25, v25
	v_rcp_f32_e32 v26, v26
	v_rcp_f32_e32 v27, v27
	v_rcp_f32_e32 v28, v28
	v_rcp_f32_e32 v29, v29
	v_rcp_f32_e32 v30, v30
	v_rcp_f32_e32 v31, v31
	s_nop 0
	v_cvt_pk_bf16_f32 v0, v0, v1
	v_cvt_pk_bf16_f32 v1, v2, v3
	v_cvt_pk_bf16_f32 v2, v4, v5
	v_cvt_pk_bf16_f32 v3, v6, v7
	v_cvt_pk_bf16_f32 v4, v8, v9
	v_cvt_pk_bf16_f32 v5, v10, v11
	v_cvt_pk_bf16_f32 v6, v12, v13
	v_cvt_pk_bf16_f32 v7, v14, v15
	v_cvt_pk_bf16_f32 v16, v16, v17
	v_cvt_pk_bf16_f32 v17, v18, v19
	v_cvt_pk_bf16_f32 v18, v20, v21
	v_cvt_pk_bf16_f32 v19, v22, v23
	v_cvt_pk_bf16_f32 v20, v24, v25
	v_cvt_pk_bf16_f32 v21, v26, v27
	v_cvt_pk_bf16_f32 v22, v28, v29
	v_cvt_pk_bf16_f32 v23, v30, v31
	v_permlane32_swap_b32_e32 v0, v2
	v_permlane32_swap_b32_e32 v1, v3
	v_permlane32_swap_b32_e32 v4, v6
	v_permlane32_swap_b32_e32 v5, v7
	v_permlane32_swap_b32_e32 v16, v18
	v_permlane32_swap_b32_e32 v17, v19
	v_permlane32_swap_b32_e32 v20, v22
	v_permlane32_swap_b32_e32 v21, v23
	global_store_dwordx4 v181, v[0:3], s[74:75] offset:0
	global_store_dwordx4 v181, v[4:7], s[74:75] offset:32
	global_store_dwordx4 v181, v[16:19], s[74:75] offset:64
	global_store_dwordx4 v181, v[20:23], s[74:75] offset:96
	s_add_u32 s74, s74, 0x44000
	s_addc_u32 s75, s75, 0
	v_pk_fma_f32 v[32:33], v[32:33], v[172:173], v[198:199] op_sel:[0,1,0] op_sel_hi:[1,1,1]
	v_pk_fma_f32 v[34:35], v[34:35], v[172:173], v[200:201] op_sel:[0,1,0] op_sel_hi:[1,1,1]
	v_pk_fma_f32 v[36:37], v[36:37], v[172:173], v[202:203] op_sel:[0,1,0] op_sel_hi:[1,1,1]
	v_pk_fma_f32 v[38:39], v[38:39], v[172:173], v[204:205] op_sel:[0,1,0] op_sel_hi:[1,1,1]
	v_pk_fma_f32 v[40:41], v[40:41], v[172:173], v[206:207] op_sel:[0,1,0] op_sel_hi:[1,1,1]
	v_pk_fma_f32 v[42:43], v[42:43], v[172:173], v[208:209] op_sel:[0,1,0] op_sel_hi:[1,1,1]
	v_pk_fma_f32 v[44:45], v[44:45], v[172:173], v[210:211] op_sel:[0,1,0] op_sel_hi:[1,1,1]
	v_pk_fma_f32 v[46:47], v[46:47], v[172:173], v[212:213] op_sel:[0,1,0] op_sel_hi:[1,1,1]
	v_pk_fma_f32 v[48:49], v[48:49], v[172:173], v[214:215] op_sel:[0,1,0] op_sel_hi:[1,1,1]
	v_pk_fma_f32 v[50:51], v[50:51], v[172:173], v[216:217] op_sel:[0,1,0] op_sel_hi:[1,1,1]
	v_pk_fma_f32 v[52:53], v[52:53], v[172:173], v[218:219] op_sel:[0,1,0] op_sel_hi:[1,1,1]
	v_pk_fma_f32 v[54:55], v[54:55], v[172:173], v[220:221] op_sel:[0,1,0] op_sel_hi:[1,1,1]
	v_pk_fma_f32 v[56:57], v[56:57], v[172:173], v[222:223] op_sel:[0,1,0] op_sel_hi:[1,1,1]
	v_pk_fma_f32 v[58:59], v[58:59], v[172:173], v[224:225] op_sel:[0,1,0] op_sel_hi:[1,1,1]
	v_pk_fma_f32 v[60:61], v[60:61], v[172:173], v[226:227] op_sel:[0,1,0] op_sel_hi:[1,1,1]
	v_pk_fma_f32 v[62:63], v[62:63], v[172:173], v[228:229] op_sel:[0,1,0] op_sel_hi:[1,1,1]
	v_exp_f32_e32 v32, v32
	v_exp_f32_e32 v33, v33
	v_exp_f32_e32 v34, v34
	v_exp_f32_e32 v35, v35
	v_exp_f32_e32 v36, v36
	v_exp_f32_e32 v37, v37
	v_exp_f32_e32 v38, v38
	v_exp_f32_e32 v39, v39
	v_exp_f32_e32 v40, v40
	v_exp_f32_e32 v41, v41
	v_exp_f32_e32 v42, v42
	v_exp_f32_e32 v43, v43
	v_exp_f32_e32 v44, v44
	v_exp_f32_e32 v45, v45
	v_exp_f32_e32 v46, v46
	v_exp_f32_e32 v47, v47
	v_exp_f32_e32 v48, v48
	v_exp_f32_e32 v49, v49
	v_exp_f32_e32 v50, v50
	v_exp_f32_e32 v51, v51
	v_exp_f32_e32 v52, v52
	v_exp_f32_e32 v53, v53
	v_exp_f32_e32 v54, v54
	v_exp_f32_e32 v55, v55
	v_exp_f32_e32 v56, v56
	v_exp_f32_e32 v57, v57
	v_exp_f32_e32 v58, v58
	v_exp_f32_e32 v59, v59
	v_exp_f32_e32 v60, v60
	v_exp_f32_e32 v61, v61
	v_exp_f32_e32 v62, v62
	v_exp_f32_e32 v63, v63
	v_pk_add_f32 v[32:33], v[32:33], 1.0 op_sel_hi:[1,0]
	v_pk_add_f32 v[34:35], v[34:35], 1.0 op_sel_hi:[1,0]
	v_pk_add_f32 v[36:37], v[36:37], 1.0 op_sel_hi:[1,0]
	v_pk_add_f32 v[38:39], v[38:39], 1.0 op_sel_hi:[1,0]
	v_pk_add_f32 v[40:41], v[40:41], 1.0 op_sel_hi:[1,0]
	v_pk_add_f32 v[42:43], v[42:43], 1.0 op_sel_hi:[1,0]
	v_pk_add_f32 v[44:45], v[44:45], 1.0 op_sel_hi:[1,0]
	v_pk_add_f32 v[46:47], v[46:47], 1.0 op_sel_hi:[1,0]
	v_pk_add_f32 v[48:49], v[48:49], 1.0 op_sel_hi:[1,0]
	v_pk_add_f32 v[50:51], v[50:51], 1.0 op_sel_hi:[1,0]
	v_pk_add_f32 v[52:53], v[52:53], 1.0 op_sel_hi:[1,0]
	v_pk_add_f32 v[54:55], v[54:55], 1.0 op_sel_hi:[1,0]
	v_pk_add_f32 v[56:57], v[56:57], 1.0 op_sel_hi:[1,0]
	v_pk_add_f32 v[58:59], v[58:59], 1.0 op_sel_hi:[1,0]
	v_pk_add_f32 v[60:61], v[60:61], 1.0 op_sel_hi:[1,0]
	v_pk_add_f32 v[62:63], v[62:63], 1.0 op_sel_hi:[1,0]
	v_rcp_f32_e32 v32, v32
	v_rcp_f32_e32 v33, v33
	v_rcp_f32_e32 v34, v34
	v_rcp_f32_e32 v35, v35
	v_rcp_f32_e32 v36, v36
	v_rcp_f32_e32 v37, v37
	v_rcp_f32_e32 v38, v38
	v_rcp_f32_e32 v39, v39
	v_rcp_f32_e32 v40, v40
	v_rcp_f32_e32 v41, v41
	v_rcp_f32_e32 v42, v42
	v_rcp_f32_e32 v43, v43
	v_rcp_f32_e32 v44, v44
	v_rcp_f32_e32 v45, v45
	v_rcp_f32_e32 v46, v46
	v_rcp_f32_e32 v47, v47
	v_rcp_f32_e32 v48, v48
	v_rcp_f32_e32 v49, v49
	v_rcp_f32_e32 v50, v50
	v_rcp_f32_e32 v51, v51
	v_rcp_f32_e32 v52, v52
	v_rcp_f32_e32 v53, v53
	v_rcp_f32_e32 v54, v54
	v_rcp_f32_e32 v55, v55
	v_rcp_f32_e32 v56, v56
	v_rcp_f32_e32 v57, v57
	v_rcp_f32_e32 v58, v58
	v_rcp_f32_e32 v59, v59
	v_rcp_f32_e32 v60, v60
	v_rcp_f32_e32 v61, v61
	v_rcp_f32_e32 v62, v62
	v_rcp_f32_e32 v63, v63
	s_nop 0
	v_cvt_pk_bf16_f32 v32, v32, v33
	v_cvt_pk_bf16_f32 v33, v34, v35
	v_cvt_pk_bf16_f32 v34, v36, v37
	v_cvt_pk_bf16_f32 v35, v38, v39
	v_cvt_pk_bf16_f32 v36, v40, v41
	v_cvt_pk_bf16_f32 v37, v42, v43
	v_cvt_pk_bf16_f32 v38, v44, v45
	v_cvt_pk_bf16_f32 v39, v46, v47
	v_cvt_pk_bf16_f32 v48, v48, v49
	v_cvt_pk_bf16_f32 v49, v50, v51
	v_cvt_pk_bf16_f32 v50, v52, v53
	v_cvt_pk_bf16_f32 v51, v54, v55
	v_cvt_pk_bf16_f32 v52, v56, v57
	v_cvt_pk_bf16_f32 v53, v58, v59
	v_cvt_pk_bf16_f32 v54, v60, v61
	v_cvt_pk_bf16_f32 v55, v62, v63
	v_permlane32_swap_b32_e32 v32, v34
	v_permlane32_swap_b32_e32 v33, v35
	v_permlane32_swap_b32_e32 v36, v38
	v_permlane32_swap_b32_e32 v37, v39
	v_permlane32_swap_b32_e32 v48, v50
	v_permlane32_swap_b32_e32 v49, v51
	v_permlane32_swap_b32_e32 v52, v54
	v_permlane32_swap_b32_e32 v53, v55
	global_store_dwordx4 v181, v[32:35], s[74:75] offset:0
	global_store_dwordx4 v181, v[36:39], s[74:75] offset:32
	global_store_dwordx4 v181, v[48:51], s[74:75] offset:64
	global_store_dwordx4 v181, v[52:55], s[74:75] offset:96
	s_add_u32 s74, s74, 0x44000
	s_addc_u32 s75, s75, 0
	v_pk_fma_f32 v[64:65], v[64:65], v[174:175], v[198:199] op_sel_hi:[1,0,1]
	v_pk_fma_f32 v[66:67], v[66:67], v[174:175], v[200:201] op_sel_hi:[1,0,1]
	v_pk_fma_f32 v[68:69], v[68:69], v[174:175], v[202:203] op_sel_hi:[1,0,1]
	v_pk_fma_f32 v[70:71], v[70:71], v[174:175], v[204:205] op_sel_hi:[1,0,1]
	v_pk_fma_f32 v[72:73], v[72:73], v[174:175], v[206:207] op_sel_hi:[1,0,1]
	v_pk_fma_f32 v[74:75], v[74:75], v[174:175], v[208:209] op_sel_hi:[1,0,1]
	v_pk_fma_f32 v[76:77], v[76:77], v[174:175], v[210:211] op_sel_hi:[1,0,1]
	v_pk_fma_f32 v[78:79], v[78:79], v[174:175], v[212:213] op_sel_hi:[1,0,1]
	v_pk_fma_f32 v[80:81], v[80:81], v[174:175], v[214:215] op_sel_hi:[1,0,1]
	v_pk_fma_f32 v[82:83], v[82:83], v[174:175], v[216:217] op_sel_hi:[1,0,1]
	v_pk_fma_f32 v[84:85], v[84:85], v[174:175], v[218:219] op_sel_hi:[1,0,1]
	v_pk_fma_f32 v[86:87], v[86:87], v[174:175], v[220:221] op_sel_hi:[1,0,1]
	v_pk_fma_f32 v[88:89], v[88:89], v[174:175], v[222:223] op_sel_hi:[1,0,1]
	v_pk_fma_f32 v[90:91], v[90:91], v[174:175], v[224:225] op_sel_hi:[1,0,1]
	v_pk_fma_f32 v[92:93], v[92:93], v[174:175], v[226:227] op_sel_hi:[1,0,1]
	v_pk_fma_f32 v[94:95], v[94:95], v[174:175], v[228:229] op_sel_hi:[1,0,1]
	v_exp_f32_e32 v64, v64
	v_exp_f32_e32 v65, v65
	v_exp_f32_e32 v66, v66
	v_exp_f32_e32 v67, v67
	v_exp_f32_e32 v68, v68
	v_exp_f32_e32 v69, v69
	v_exp_f32_e32 v70, v70
	v_exp_f32_e32 v71, v71
	v_exp_f32_e32 v72, v72
	v_exp_f32_e32 v73, v73
	v_exp_f32_e32 v74, v74
	v_exp_f32_e32 v75, v75
	v_exp_f32_e32 v76, v76
	v_exp_f32_e32 v77, v77
	v_exp_f32_e32 v78, v78
	v_exp_f32_e32 v79, v79
	v_exp_f32_e32 v80, v80
	v_exp_f32_e32 v81, v81
	v_exp_f32_e32 v82, v82
	v_exp_f32_e32 v83, v83
	v_exp_f32_e32 v84, v84
	v_exp_f32_e32 v85, v85
	v_exp_f32_e32 v86, v86
	v_exp_f32_e32 v87, v87
	v_exp_f32_e32 v88, v88
	v_exp_f32_e32 v89, v89
	v_exp_f32_e32 v90, v90
	v_exp_f32_e32 v91, v91
	v_exp_f32_e32 v92, v92
	v_exp_f32_e32 v93, v93
	v_exp_f32_e32 v94, v94
	v_exp_f32_e32 v95, v95
	v_pk_add_f32 v[64:65], v[64:65], 1.0 op_sel_hi:[1,0]
	v_pk_add_f32 v[66:67], v[66:67], 1.0 op_sel_hi:[1,0]
	v_pk_add_f32 v[68:69], v[68:69], 1.0 op_sel_hi:[1,0]
	v_pk_add_f32 v[70:71], v[70:71], 1.0 op_sel_hi:[1,0]
	v_pk_add_f32 v[72:73], v[72:73], 1.0 op_sel_hi:[1,0]
	v_pk_add_f32 v[74:75], v[74:75], 1.0 op_sel_hi:[1,0]
	v_pk_add_f32 v[76:77], v[76:77], 1.0 op_sel_hi:[1,0]
	v_pk_add_f32 v[78:79], v[78:79], 1.0 op_sel_hi:[1,0]
	v_pk_add_f32 v[80:81], v[80:81], 1.0 op_sel_hi:[1,0]
	v_pk_add_f32 v[82:83], v[82:83], 1.0 op_sel_hi:[1,0]
	v_pk_add_f32 v[84:85], v[84:85], 1.0 op_sel_hi:[1,0]
	v_pk_add_f32 v[86:87], v[86:87], 1.0 op_sel_hi:[1,0]
	v_pk_add_f32 v[88:89], v[88:89], 1.0 op_sel_hi:[1,0]
	v_pk_add_f32 v[90:91], v[90:91], 1.0 op_sel_hi:[1,0]
	v_pk_add_f32 v[92:93], v[92:93], 1.0 op_sel_hi:[1,0]
	v_pk_add_f32 v[94:95], v[94:95], 1.0 op_sel_hi:[1,0]
	v_rcp_f32_e32 v64, v64
	v_rcp_f32_e32 v65, v65
	v_rcp_f32_e32 v66, v66
	v_rcp_f32_e32 v67, v67
	v_rcp_f32_e32 v68, v68
	v_rcp_f32_e32 v69, v69
	v_rcp_f32_e32 v70, v70
	v_rcp_f32_e32 v71, v71
	v_rcp_f32_e32 v72, v72
	v_rcp_f32_e32 v73, v73
	v_rcp_f32_e32 v74, v74
	v_rcp_f32_e32 v75, v75
	v_rcp_f32_e32 v76, v76
	v_rcp_f32_e32 v77, v77
	v_rcp_f32_e32 v78, v78
	v_rcp_f32_e32 v79, v79
	v_rcp_f32_e32 v80, v80
	v_rcp_f32_e32 v81, v81
	v_rcp_f32_e32 v82, v82
	v_rcp_f32_e32 v83, v83
	v_rcp_f32_e32 v84, v84
	v_rcp_f32_e32 v85, v85
	v_rcp_f32_e32 v86, v86
	v_rcp_f32_e32 v87, v87
	v_rcp_f32_e32 v88, v88
	v_rcp_f32_e32 v89, v89
	v_rcp_f32_e32 v90, v90
	v_rcp_f32_e32 v91, v91
	v_rcp_f32_e32 v92, v92
	v_rcp_f32_e32 v93, v93
	v_rcp_f32_e32 v94, v94
	v_rcp_f32_e32 v95, v95
	s_nop 0
	v_cvt_pk_bf16_f32 v64, v64, v65
	v_cvt_pk_bf16_f32 v65, v66, v67
	v_cvt_pk_bf16_f32 v66, v68, v69
	v_cvt_pk_bf16_f32 v67, v70, v71
	v_cvt_pk_bf16_f32 v68, v72, v73
	v_cvt_pk_bf16_f32 v69, v74, v75
	v_cvt_pk_bf16_f32 v70, v76, v77
	v_cvt_pk_bf16_f32 v71, v78, v79
	v_cvt_pk_bf16_f32 v80, v80, v81
	v_cvt_pk_bf16_f32 v81, v82, v83
	v_cvt_pk_bf16_f32 v82, v84, v85
	v_cvt_pk_bf16_f32 v83, v86, v87
	v_cvt_pk_bf16_f32 v84, v88, v89
	v_cvt_pk_bf16_f32 v85, v90, v91
	v_cvt_pk_bf16_f32 v86, v92, v93
	v_cvt_pk_bf16_f32 v87, v94, v95
	v_permlane32_swap_b32_e32 v64, v66
	v_permlane32_swap_b32_e32 v65, v67
	v_permlane32_swap_b32_e32 v68, v70
	v_permlane32_swap_b32_e32 v69, v71
	v_permlane32_swap_b32_e32 v80, v82
	v_permlane32_swap_b32_e32 v81, v83
	v_permlane32_swap_b32_e32 v84, v86
	v_permlane32_swap_b32_e32 v85, v87
	global_store_dwordx4 v181, v[64:67], s[74:75] offset:0
	global_store_dwordx4 v181, v[68:71], s[74:75] offset:32
	global_store_dwordx4 v181, v[80:83], s[74:75] offset:64
	global_store_dwordx4 v181, v[84:87], s[74:75] offset:96
	s_add_u32 s74, s74, 0x44000
	s_addc_u32 s75, s75, 0
	v_pk_fma_f32 v[96:97], v[96:97], v[174:175], v[198:199] op_sel:[0,1,0] op_sel_hi:[1,1,1]
	v_pk_fma_f32 v[98:99], v[98:99], v[174:175], v[200:201] op_sel:[0,1,0] op_sel_hi:[1,1,1]
	v_pk_fma_f32 v[100:101], v[100:101], v[174:175], v[202:203] op_sel:[0,1,0] op_sel_hi:[1,1,1]
	v_pk_fma_f32 v[102:103], v[102:103], v[174:175], v[204:205] op_sel:[0,1,0] op_sel_hi:[1,1,1]
	v_pk_fma_f32 v[104:105], v[104:105], v[174:175], v[206:207] op_sel:[0,1,0] op_sel_hi:[1,1,1]
	v_pk_fma_f32 v[106:107], v[106:107], v[174:175], v[208:209] op_sel:[0,1,0] op_sel_hi:[1,1,1]
	v_pk_fma_f32 v[108:109], v[108:109], v[174:175], v[210:211] op_sel:[0,1,0] op_sel_hi:[1,1,1]
	v_pk_fma_f32 v[110:111], v[110:111], v[174:175], v[212:213] op_sel:[0,1,0] op_sel_hi:[1,1,1]
	v_pk_fma_f32 v[112:113], v[112:113], v[174:175], v[214:215] op_sel:[0,1,0] op_sel_hi:[1,1,1]
	v_pk_fma_f32 v[114:115], v[114:115], v[174:175], v[216:217] op_sel:[0,1,0] op_sel_hi:[1,1,1]
	v_pk_fma_f32 v[116:117], v[116:117], v[174:175], v[218:219] op_sel:[0,1,0] op_sel_hi:[1,1,1]
	v_pk_fma_f32 v[118:119], v[118:119], v[174:175], v[220:221] op_sel:[0,1,0] op_sel_hi:[1,1,1]
	v_pk_fma_f32 v[120:121], v[120:121], v[174:175], v[222:223] op_sel:[0,1,0] op_sel_hi:[1,1,1]
	v_pk_fma_f32 v[122:123], v[122:123], v[174:175], v[224:225] op_sel:[0,1,0] op_sel_hi:[1,1,1]
	v_pk_fma_f32 v[124:125], v[124:125], v[174:175], v[226:227] op_sel:[0,1,0] op_sel_hi:[1,1,1]
	v_pk_fma_f32 v[126:127], v[126:127], v[174:175], v[228:229] op_sel:[0,1,0] op_sel_hi:[1,1,1]
	v_exp_f32_e32 v96, v96
	v_exp_f32_e32 v97, v97
	v_exp_f32_e32 v98, v98
	v_exp_f32_e32 v99, v99
	v_exp_f32_e32 v100, v100
	v_exp_f32_e32 v101, v101
	v_exp_f32_e32 v102, v102
	v_exp_f32_e32 v103, v103
	v_exp_f32_e32 v104, v104
	v_exp_f32_e32 v105, v105
	v_exp_f32_e32 v106, v106
	v_exp_f32_e32 v107, v107
	v_exp_f32_e32 v108, v108
	v_exp_f32_e32 v109, v109
	v_exp_f32_e32 v110, v110
	v_exp_f32_e32 v111, v111
	v_exp_f32_e32 v112, v112
	v_exp_f32_e32 v113, v113
	v_exp_f32_e32 v114, v114
	v_exp_f32_e32 v115, v115
	v_exp_f32_e32 v116, v116
	v_exp_f32_e32 v117, v117
	v_exp_f32_e32 v118, v118
	v_exp_f32_e32 v119, v119
	v_exp_f32_e32 v120, v120
	v_exp_f32_e32 v121, v121
	v_exp_f32_e32 v122, v122
	v_exp_f32_e32 v123, v123
	v_exp_f32_e32 v124, v124
	v_exp_f32_e32 v125, v125
	v_exp_f32_e32 v126, v126
	v_exp_f32_e32 v127, v127
	v_pk_add_f32 v[96:97], v[96:97], 1.0 op_sel_hi:[1,0]
	v_pk_add_f32 v[98:99], v[98:99], 1.0 op_sel_hi:[1,0]
	v_pk_add_f32 v[100:101], v[100:101], 1.0 op_sel_hi:[1,0]
	v_pk_add_f32 v[102:103], v[102:103], 1.0 op_sel_hi:[1,0]
	v_pk_add_f32 v[104:105], v[104:105], 1.0 op_sel_hi:[1,0]
	v_pk_add_f32 v[106:107], v[106:107], 1.0 op_sel_hi:[1,0]
	v_pk_add_f32 v[108:109], v[108:109], 1.0 op_sel_hi:[1,0]
	v_pk_add_f32 v[110:111], v[110:111], 1.0 op_sel_hi:[1,0]
	v_pk_add_f32 v[112:113], v[112:113], 1.0 op_sel_hi:[1,0]
	v_pk_add_f32 v[114:115], v[114:115], 1.0 op_sel_hi:[1,0]
	v_pk_add_f32 v[116:117], v[116:117], 1.0 op_sel_hi:[1,0]
	v_pk_add_f32 v[118:119], v[118:119], 1.0 op_sel_hi:[1,0]
	v_pk_add_f32 v[120:121], v[120:121], 1.0 op_sel_hi:[1,0]
	v_pk_add_f32 v[122:123], v[122:123], 1.0 op_sel_hi:[1,0]
	v_pk_add_f32 v[124:125], v[124:125], 1.0 op_sel_hi:[1,0]
	v_pk_add_f32 v[126:127], v[126:127], 1.0 op_sel_hi:[1,0]
	v_rcp_f32_e32 v96, v96
	v_rcp_f32_e32 v97, v97
	v_rcp_f32_e32 v98, v98
	v_rcp_f32_e32 v99, v99
	v_rcp_f32_e32 v100, v100
	v_rcp_f32_e32 v101, v101
	v_rcp_f32_e32 v102, v102
	v_rcp_f32_e32 v103, v103
	v_rcp_f32_e32 v104, v104
	v_rcp_f32_e32 v105, v105
	v_rcp_f32_e32 v106, v106
	v_rcp_f32_e32 v107, v107
	v_rcp_f32_e32 v108, v108
	v_rcp_f32_e32 v109, v109
	v_rcp_f32_e32 v110, v110
	v_rcp_f32_e32 v111, v111
	v_rcp_f32_e32 v112, v112
	v_rcp_f32_e32 v113, v113
	v_rcp_f32_e32 v114, v114
	v_rcp_f32_e32 v115, v115
	v_rcp_f32_e32 v116, v116
	v_rcp_f32_e32 v117, v117
	v_rcp_f32_e32 v118, v118
	v_rcp_f32_e32 v119, v119
	v_rcp_f32_e32 v120, v120
	v_rcp_f32_e32 v121, v121
	v_rcp_f32_e32 v122, v122
	v_rcp_f32_e32 v123, v123
	v_rcp_f32_e32 v124, v124
	v_rcp_f32_e32 v125, v125
	v_rcp_f32_e32 v126, v126
	v_rcp_f32_e32 v127, v127
	s_nop 0
	v_cvt_pk_bf16_f32 v96, v96, v97
	v_cvt_pk_bf16_f32 v97, v98, v99
	v_cvt_pk_bf16_f32 v98, v100, v101
	v_cvt_pk_bf16_f32 v99, v102, v103
	v_cvt_pk_bf16_f32 v100, v104, v105
	v_cvt_pk_bf16_f32 v101, v106, v107
	v_cvt_pk_bf16_f32 v102, v108, v109
	v_cvt_pk_bf16_f32 v103, v110, v111
	v_cvt_pk_bf16_f32 v112, v112, v113
	v_cvt_pk_bf16_f32 v113, v114, v115
	v_cvt_pk_bf16_f32 v114, v116, v117
	v_cvt_pk_bf16_f32 v115, v118, v119
	v_cvt_pk_bf16_f32 v116, v120, v121
	v_cvt_pk_bf16_f32 v117, v122, v123
	v_cvt_pk_bf16_f32 v118, v124, v125
	v_cvt_pk_bf16_f32 v119, v126, v127
	v_permlane32_swap_b32_e32 v96, v98
	v_permlane32_swap_b32_e32 v97, v99
	v_permlane32_swap_b32_e32 v100, v102
	v_permlane32_swap_b32_e32 v101, v103
	v_permlane32_swap_b32_e32 v112, v114
	v_permlane32_swap_b32_e32 v113, v115
	v_permlane32_swap_b32_e32 v116, v118
	v_permlane32_swap_b32_e32 v117, v119
	global_store_dwordx4 v181, v[96:99], s[74:75] offset:0
	global_store_dwordx4 v181, v[100:103], s[74:75] offset:32
	global_store_dwordx4 v181, v[112:115], s[74:75] offset:64
	global_store_dwordx4 v181, v[116:119], s[74:75] offset:96
	s_branch .Lpe_ret_L0
.Lpe_vt_L0:
	s_lshl_b32 s35, s34, 2
	s_add_u32 s35, s35, s28
	s_add_u32 s36, s28, 6
	s_cmp_eq_u32 s25, 8
	s_cselect_b32 s35, s36, s35
	s_lshr_b32 s36, s29, 11
	s_mul_i32 s36, s36, 10
	s_add_u32 s36, s36, s35
	s_lshl_b32 s36, s36, 18
	s_and_b32 s37, s29, 0x7ff
	s_lshl_b32 s37, s37, 1
	s_add_u32 s36, s36, s37
	s_add_u32 s38, s72, 0x14920000
	s_addc_u32 s39, s73, 0
	s_add_u32 s38, s38, s36
	s_addc_u32 s39, s39, 0
	s_mul_i32 s36, s26, 10240
	s_add_u32 s36, s36, 0x10000
	v_lshlrev_b32_e32 v180, 1, v197
	v_mul_u32_u24_e32 v181, 36, v146
	v_add3_u32 v180, v180, v181, s36
	v_lshrrev_b32_e32 v181, 3, v179
	v_and_b32_e32 v146, 7, v179
	v_lshlrev_b32_e32 v146, 4, v146
	v_mul_u32_u24_e32 v198, 144, v181
	v_add3_u32 v198, v198, v146, s36
	v_lshl_add_u32 v199, v181, 12, v146
	s_waitcnt vmcnt(0)
	v_mov_b32_e32 v197, 0x358637bd
	v_pk_add_f32 v[128:129], v[128:129], v[130:131]
	v_pk_add_f32 v[132:133], v[132:133], v[134:135]
	v_pk_add_f32 v[136:137], v[136:137], v[138:139]
	v_pk_add_f32 v[140:141], v[140:141], v[142:143]
	v_pk_add_f32 v[164:165], v[164:165], v[166:167]
	v_pk_add_f32 v[168:169], v[168:169], v[170:171]
	v_pk_add_f32 v[246:247], v[246:247], v[248:249]
	v_pk_add_f32 v[250:251], v[250:251], v[252:253]
	v_pk_add_f32 v[128:129], v[128:129], v[132:133]
	v_pk_add_f32 v[136:137], v[136:137], v[140:141]
	v_pk_add_f32 v[164:165], v[164:165], v[168:169]
	v_pk_add_f32 v[246:247], v[246:247], v[250:251]
	v_add_f32_e32 v128, v128, v129
	v_add_f32_e32 v136, v136, v137
	v_add_f32_e32 v164, v164, v165
	v_add_f32_e32 v246, v246, v247
	v_fmamk_f32 v128, v128, 0x3a800000, v197
	v_fmamk_f32 v136, v136, 0x3a800000, v197
	v_fmamk_f32 v164, v164, 0x3a800000, v197
	v_fmamk_f32 v246, v246, 0x3a800000, v197
	v_rsq_f32_e32 v172, v128
	v_rsq_f32_e32 v173, v136
	v_rsq_f32_e32 v174, v164
	v_rsq_f32_e32 v175, v246
	s_nop 0
	s_add_u32 s76, s99, s90
	s_cmp_lt_u32 s76, 0x440
	s_cselect_b32 s80, 1, 0
	s_cselect_b32 s83, 0x200000, 0
	s_lshl_b32 s76, s24, 19
	s_lshl_b32 s77, s26, 16
	s_add_u32 s76, s76, s77
	s_and_b32 s77, s24, 7
	s_lshl_b32 s77, s77, 8
	s_and_b32 s82, s25, 3
	s_lshl_b32 s82, s82, 9
	s_add_u32 s77, s77, s82
	s_and_b32 s77, s77, 0x7ff
	s_add_u32 s76, s76, s77
	s_add_u32 s78, s72, 0xa120000
	s_addc_u32 s79, s73, 0
	s_add_u32 s78, s78, s76
	s_addc_u32 s79, s79, 0
	s_lshl_b32 s76, s25, 19
	s_add_u32 s76, s76, s83
	s_add_u32 s76, s76, s77
	s_lshl_b32 s77, s26, 16
	s_add_u32 s76, s76, s77
	s_add_u32 s82, s72, 0x0
	s_addc_u32 s83, s73, 0
	s_add_u32 s82, s82, s76
	s_addc_u32 s83, s83, 0
	s_lshl_b32 s76, s26, 12
	s_mov_b32 m0, s76
	s_nop 0
	global_load_lds_dwordx4 v145, s[78:79]
	s_add_u32 s78, s78, 0x4000
	s_addc_u32 s79, s79, 0
	s_add_u32 s76, s76, 0x400
	s_mov_b32 m0, s76
	s_nop 0
	global_load_lds_dwordx4 v185, s[78:79]
	s_add_u32 s78, s78, 0x4000
	s_addc_u32 s79, s79, 0
	s_add_u32 s76, s76, 0x400
	s_mov_b32 m0, s76
	s_nop 0
	global_load_lds_dwordx4 v145, s[78:79]
	s_add_u32 s78, s78, 0x4000
	s_addc_u32 s79, s79, 0
	s_add_u32 s76, s76, 0x400
	s_mov_b32 m0, s76
	s_nop 0
	global_load_lds_dwordx4 v185, s[78:79]
	s_add_u32 s78, s78, 0x4000
	s_addc_u32 s79, s79, 0
	s_add_u32 s76, s76, 0x400
	s_add_u32 s76, s76, 0x7000
	s_mov_b32 m0, s76
	s_nop 0
	global_load_lds_dwordx4 v145, s[82:83]
	s_add_u32 s82, s82, 0x4000
	s_addc_u32 s83, s83, 0
	s_add_u32 s76, s76, 0x400
	s_mov_b32 m0, s76
	s_nop 0
	global_load_lds_dwordx4 v185, s[82:83]
	s_add_u32 s82, s82, 0x4000
	s_addc_u32 s83, s83, 0
	s_add_u32 s76, s76, 0x400
	s_mov_b32 m0, s76
	s_nop 0
	global_load_lds_dwordx4 v145, s[82:83]
	s_add_u32 s82, s82, 0x4000
	s_addc_u32 s83, s83, 0
	s_add_u32 s76, s76, 0x400
	s_mov_b32 m0, s76
	s_nop 0
	global_load_lds_dwordx4 v185, s[82:83]
	s_add_u32 s82, s82, 0x4000
	s_addc_u32 s83, s83, 0
	s_add_u32 s76, s76, 0x400
	v_pk_mul_f32 v[0:1], v[0:1], v[172:173] op_sel_hi:[1,0]
	v_pk_mul_f32 v[2:3], v[2:3], v[172:173] op_sel_hi:[1,0]
	v_pk_mul_f32 v[4:5], v[4:5], v[172:173] op_sel_hi:[1,0]
	v_pk_mul_f32 v[6:7], v[6:7], v[172:173] op_sel_hi:[1,0]
	v_pk_mul_f32 v[8:9], v[8:9], v[172:173] op_sel_hi:[1,0]
	v_pk_mul_f32 v[10:11], v[10:11], v[172:173] op_sel_hi:[1,0]
	v_pk_mul_f32 v[12:13], v[12:13], v[172:173] op_sel_hi:[1,0]
	v_pk_mul_f32 v[14:15], v[14:15], v[172:173] op_sel_hi:[1,0]
	v_pk_mul_f32 v[16:17], v[16:17], v[172:173] op_sel_hi:[1,0]
	v_pk_mul_f32 v[18:19], v[18:19], v[172:173] op_sel_hi:[1,0]
	v_pk_mul_f32 v[20:21], v[20:21], v[172:173] op_sel_hi:[1,0]
	v_pk_mul_f32 v[22:23], v[22:23], v[172:173] op_sel_hi:[1,0]
	v_pk_mul_f32 v[24:25], v[24:25], v[172:173] op_sel_hi:[1,0]
	v_pk_mul_f32 v[26:27], v[26:27], v[172:173] op_sel_hi:[1,0]
	v_pk_mul_f32 v[28:29], v[28:29], v[172:173] op_sel_hi:[1,0]
	v_pk_mul_f32 v[30:31], v[30:31], v[172:173] op_sel_hi:[1,0]
	v_pk_mul_f32 v[32:33], v[32:33], v[172:173] op_sel:[0,1] op_sel_hi:[1,1]
	v_pk_mul_f32 v[34:35], v[34:35], v[172:173] op_sel:[0,1] op_sel_hi:[1,1]
	v_pk_mul_f32 v[36:37], v[36:37], v[172:173] op_sel:[0,1] op_sel_hi:[1,1]
	v_pk_mul_f32 v[38:39], v[38:39], v[172:173] op_sel:[0,1] op_sel_hi:[1,1]
	v_pk_mul_f32 v[40:41], v[40:41], v[172:173] op_sel:[0,1] op_sel_hi:[1,1]
	v_pk_mul_f32 v[42:43], v[42:43], v[172:173] op_sel:[0,1] op_sel_hi:[1,1]
	v_pk_mul_f32 v[44:45], v[44:45], v[172:173] op_sel:[0,1] op_sel_hi:[1,1]
	v_pk_mul_f32 v[46:47], v[46:47], v[172:173] op_sel:[0,1] op_sel_hi:[1,1]
	v_pk_mul_f32 v[48:49], v[48:49], v[172:173] op_sel:[0,1] op_sel_hi:[1,1]
	v_pk_mul_f32 v[50:51], v[50:51], v[172:173] op_sel:[0,1] op_sel_hi:[1,1]
	v_pk_mul_f32 v[52:53], v[52:53], v[172:173] op_sel:[0,1] op_sel_hi:[1,1]
	v_pk_mul_f32 v[54:55], v[54:55], v[172:173] op_sel:[0,1] op_sel_hi:[1,1]
	v_pk_mul_f32 v[56:57], v[56:57], v[172:173] op_sel:[0,1] op_sel_hi:[1,1]
	v_pk_mul_f32 v[58:59], v[58:59], v[172:173] op_sel:[0,1] op_sel_hi:[1,1]
	v_pk_mul_f32 v[60:61], v[60:61], v[172:173] op_sel:[0,1] op_sel_hi:[1,1]
	v_pk_mul_f32 v[62:63], v[62:63], v[172:173] op_sel:[0,1] op_sel_hi:[1,1]
	v_pk_mul_f32 v[64:65], v[64:65], v[174:175] op_sel_hi:[1,0]
	v_pk_mul_f32 v[66:67], v[66:67], v[174:175] op_sel_hi:[1,0]
	v_pk_mul_f32 v[68:69], v[68:69], v[174:175] op_sel_hi:[1,0]
	v_pk_mul_f32 v[70:71], v[70:71], v[174:175] op_sel_hi:[1,0]
	v_pk_mul_f32 v[72:73], v[72:73], v[174:175] op_sel_hi:[1,0]
	v_pk_mul_f32 v[74:75], v[74:75], v[174:175] op_sel_hi:[1,0]
	v_pk_mul_f32 v[76:77], v[76:77], v[174:175] op_sel_hi:[1,0]
	v_pk_mul_f32 v[78:79], v[78:79], v[174:175] op_sel_hi:[1,0]
	v_pk_mul_f32 v[80:81], v[80:81], v[174:175] op_sel_hi:[1,0]
	v_pk_mul_f32 v[82:83], v[82:83], v[174:175] op_sel_hi:[1,0]
	v_pk_mul_f32 v[84:85], v[84:85], v[174:175] op_sel_hi:[1,0]
	v_pk_mul_f32 v[86:87], v[86:87], v[174:175] op_sel_hi:[1,0]
	v_pk_mul_f32 v[88:89], v[88:89], v[174:175] op_sel_hi:[1,0]
	v_pk_mul_f32 v[90:91], v[90:91], v[174:175] op_sel_hi:[1,0]
	v_pk_mul_f32 v[92:93], v[92:93], v[174:175] op_sel_hi:[1,0]
	v_pk_mul_f32 v[94:95], v[94:95], v[174:175] op_sel_hi:[1,0]
	v_pk_mul_f32 v[96:97], v[96:97], v[174:175] op_sel:[0,1] op_sel_hi:[1,1]
	v_pk_mul_f32 v[98:99], v[98:99], v[174:175] op_sel:[0,1] op_sel_hi:[1,1]
	v_pk_mul_f32 v[100:101], v[100:101], v[174:175] op_sel:[0,1] op_sel_hi:[1,1]
	v_pk_mul_f32 v[102:103], v[102:103], v[174:175] op_sel:[0,1] op_sel_hi:[1,1]
	v_pk_mul_f32 v[104:105], v[104:105], v[174:175] op_sel:[0,1] op_sel_hi:[1,1]
	v_pk_mul_f32 v[106:107], v[106:107], v[174:175] op_sel:[0,1] op_sel_hi:[1,1]
	v_pk_mul_f32 v[108:109], v[108:109], v[174:175] op_sel:[0,1] op_sel_hi:[1,1]
	v_pk_mul_f32 v[110:111], v[110:111], v[174:175] op_sel:[0,1] op_sel_hi:[1,1]
	v_pk_mul_f32 v[112:113], v[112:113], v[174:175] op_sel:[0,1] op_sel_hi:[1,1]
	v_pk_mul_f32 v[114:115], v[114:115], v[174:175] op_sel:[0,1] op_sel_hi:[1,1]
	v_pk_mul_f32 v[116:117], v[116:117], v[174:175] op_sel:[0,1] op_sel_hi:[1,1]
	v_pk_mul_f32 v[118:119], v[118:119], v[174:175] op_sel:[0,1] op_sel_hi:[1,1]
	v_pk_mul_f32 v[120:121], v[120:121], v[174:175] op_sel:[0,1] op_sel_hi:[1,1]
	v_pk_mul_f32 v[122:123], v[122:123], v[174:175] op_sel:[0,1] op_sel_hi:[1,1]
	v_pk_mul_f32 v[124:125], v[124:125], v[174:175] op_sel:[0,1] op_sel_hi:[1,1]
	v_pk_mul_f32 v[126:127], v[126:127], v[174:175] op_sel:[0,1] op_sel_hi:[1,1]
	v_cvt_pk_bf16_f32 v0, v0, v1
	v_cvt_pk_bf16_f32 v1, v2, v3
	v_cvt_pk_bf16_f32 v2, v4, v5
	v_cvt_pk_bf16_f32 v3, v6, v7
	v_cvt_pk_bf16_f32 v4, v8, v9
	v_cvt_pk_bf16_f32 v5, v10, v11
	v_cvt_pk_bf16_f32 v6, v12, v13
	v_cvt_pk_bf16_f32 v7, v14, v15
	ds_write_b16 v180, v0 offset:0
	ds_write_b16_d16_hi v180, v0 offset:144
	ds_write_b16 v180, v1 offset:288
	ds_write_b16_d16_hi v180, v1 offset:432
	ds_write_b16 v180, v2 offset:1152
	ds_write_b16_d16_hi v180, v2 offset:1296
	ds_write_b16 v180, v3 offset:1440
	ds_write_b16_d16_hi v180, v3 offset:1584
	ds_write_b16 v180, v4 offset:2304
	ds_write_b16_d16_hi v180, v4 offset:2448
	ds_write_b16 v180, v5 offset:2592
	ds_write_b16_d16_hi v180, v5 offset:2736
	ds_write_b16 v180, v6 offset:3456
	ds_write_b16_d16_hi v180, v6 offset:3600
	ds_write_b16 v180, v7 offset:3744
	ds_write_b16_d16_hi v180, v7 offset:3888
	v_cvt_pk_bf16_f32 v16, v16, v17
	v_cvt_pk_bf16_f32 v17, v18, v19
	v_cvt_pk_bf16_f32 v18, v20, v21
	v_cvt_pk_bf16_f32 v19, v22, v23
	v_cvt_pk_bf16_f32 v20, v24, v25
	v_cvt_pk_bf16_f32 v21, v26, v27
	v_cvt_pk_bf16_f32 v22, v28, v29
	v_cvt_pk_bf16_f32 v23, v30, v31
	ds_write_b16 v180, v16 offset:4608
	ds_write_b16_d16_hi v180, v16 offset:4752
	ds_write_b16 v180, v17 offset:4896
	ds_write_b16_d16_hi v180, v17 offset:5040
	ds_write_b16 v180, v18 offset:5760
	ds_write_b16_d16_hi v180, v18 offset:5904
	ds_write_b16 v180, v19 offset:6048
	ds_write_b16_d16_hi v180, v19 offset:6192
	ds_write_b16 v180, v20 offset:6912
	ds_write_b16_d16_hi v180, v20 offset:7056
	ds_write_b16 v180, v21 offset:7200
	ds_write_b16_d16_hi v180, v21 offset:7344
	ds_write_b16 v180, v22 offset:8064
	ds_write_b16_d16_hi v180, v22 offset:8208
	ds_write_b16 v180, v23 offset:8352
	ds_write_b16_d16_hi v180, v23 offset:8496
	v_cvt_pk_bf16_f32 v32, v32, v33
	v_cvt_pk_bf16_f32 v33, v34, v35
	v_cvt_pk_bf16_f32 v34, v36, v37
	v_cvt_pk_bf16_f32 v35, v38, v39
	v_cvt_pk_bf16_f32 v36, v40, v41
	v_cvt_pk_bf16_f32 v37, v42, v43
	v_cvt_pk_bf16_f32 v38, v44, v45
	v_cvt_pk_bf16_f32 v39, v46, v47
	ds_write_b16 v180, v32 offset:64
	ds_write_b16_d16_hi v180, v32 offset:208
	ds_write_b16 v180, v33 offset:352
	ds_write_b16_d16_hi v180, v33 offset:496
	ds_write_b16 v180, v34 offset:1216
	ds_write_b16_d16_hi v180, v34 offset:1360
	ds_write_b16 v180, v35 offset:1504
	ds_write_b16_d16_hi v180, v35 offset:1648
	ds_write_b16 v180, v36 offset:2368
	ds_write_b16_d16_hi v180, v36 offset:2512
	ds_write_b16 v180, v37 offset:2656
	ds_write_b16_d16_hi v180, v37 offset:2800
	ds_write_b16 v180, v38 offset:3520
	ds_write_b16_d16_hi v180, v38 offset:3664
	ds_write_b16 v180, v39 offset:3808
	ds_write_b16_d16_hi v180, v39 offset:3952
	v_cvt_pk_bf16_f32 v48, v48, v49
	v_cvt_pk_bf16_f32 v49, v50, v51
	v_cvt_pk_bf16_f32 v50, v52, v53
	v_cvt_pk_bf16_f32 v51, v54, v55
	v_cvt_pk_bf16_f32 v52, v56, v57
	v_cvt_pk_bf16_f32 v53, v58, v59
	v_cvt_pk_bf16_f32 v54, v60, v61
	v_cvt_pk_bf16_f32 v55, v62, v63
	ds_write_b16 v180, v48 offset:4672
	ds_write_b16_d16_hi v180, v48 offset:4816
	ds_write_b16 v180, v49 offset:4960
	ds_write_b16_d16_hi v180, v49 offset:5104
	ds_write_b16 v180, v50 offset:5824
	ds_write_b16_d16_hi v180, v50 offset:5968
	ds_write_b16 v180, v51 offset:6112
	ds_write_b16_d16_hi v180, v51 offset:6256
	ds_write_b16 v180, v52 offset:6976
	ds_write_b16_d16_hi v180, v52 offset:7120
	ds_write_b16 v180, v53 offset:7264
	ds_write_b16_d16_hi v180, v53 offset:7408
	ds_write_b16 v180, v54 offset:8128
	ds_write_b16_d16_hi v180, v54 offset:8272
	ds_write_b16 v180, v55 offset:8416
	ds_write_b16_d16_hi v180, v55 offset:8560
	s_waitcnt lgkmcnt(0)
	ds_read_b128 v[0:3], v198 offset:0
	ds_read_b128 v[4:7], v198 offset:1152
	ds_read_b128 v[8:11], v198 offset:2304
	ds_read_b128 v[12:15], v198 offset:3456
	ds_read_b128 v[16:19], v198 offset:4608
	ds_read_b128 v[20:23], v198 offset:5760
	ds_read_b128 v[24:27], v198 offset:6912
	ds_read_b128 v[28:31], v198 offset:8064
	s_waitcnt lgkmcnt(7)
	global_store_dwordx4 v199, v[0:3], s[38:39]
	s_add_u32 s38, s38, 0x8000
	s_addc_u32 s39, s39, 0
	s_waitcnt lgkmcnt(6)
	global_store_dwordx4 v199, v[4:7], s[38:39]
	s_add_u32 s38, s38, 0x8000
	s_addc_u32 s39, s39, 0
	s_waitcnt lgkmcnt(5)
	global_store_dwordx4 v199, v[8:11], s[38:39]
	s_add_u32 s38, s38, 0x8000
	s_addc_u32 s39, s39, 0
	s_waitcnt lgkmcnt(4)
	global_store_dwordx4 v199, v[12:15], s[38:39]
	s_add_u32 s38, s38, 0x8000
	s_addc_u32 s39, s39, 0
	s_waitcnt lgkmcnt(3)
	global_store_dwordx4 v199, v[16:19], s[38:39]
	s_add_u32 s38, s38, 0x8000
	s_addc_u32 s39, s39, 0
	s_waitcnt lgkmcnt(2)
	global_store_dwordx4 v199, v[20:23], s[38:39]
	s_add_u32 s38, s38, 0x8000
	s_addc_u32 s39, s39, 0
	s_waitcnt lgkmcnt(1)
	global_store_dwordx4 v199, v[24:27], s[38:39]
	s_add_u32 s38, s38, 0x8000
	s_addc_u32 s39, s39, 0
	s_waitcnt lgkmcnt(0)
	global_store_dwordx4 v199, v[28:31], s[38:39]
	s_sub_u32 s38, s38, 229248
	s_subb_u32 s39, s39, 0
	v_cvt_pk_bf16_f32 v64, v64, v65
	v_cvt_pk_bf16_f32 v65, v66, v67
	v_cvt_pk_bf16_f32 v66, v68, v69
	v_cvt_pk_bf16_f32 v67, v70, v71
	v_cvt_pk_bf16_f32 v68, v72, v73
	v_cvt_pk_bf16_f32 v69, v74, v75
	v_cvt_pk_bf16_f32 v70, v76, v77
	v_cvt_pk_bf16_f32 v71, v78, v79
	ds_write_b16 v180, v64 offset:0
	ds_write_b16_d16_hi v180, v64 offset:144
	ds_write_b16 v180, v65 offset:288
	ds_write_b16_d16_hi v180, v65 offset:432
	ds_write_b16 v180, v66 offset:1152
	ds_write_b16_d16_hi v180, v66 offset:1296
	ds_write_b16 v180, v67 offset:1440
	ds_write_b16_d16_hi v180, v67 offset:1584
	ds_write_b16 v180, v68 offset:2304
	ds_write_b16_d16_hi v180, v68 offset:2448
	ds_write_b16 v180, v69 offset:2592
	ds_write_b16_d16_hi v180, v69 offset:2736
	ds_write_b16 v180, v70 offset:3456
	ds_write_b16_d16_hi v180, v70 offset:3600
	ds_write_b16 v180, v71 offset:3744
	ds_write_b16_d16_hi v180, v71 offset:3888
	v_cvt_pk_bf16_f32 v80, v80, v81
	v_cvt_pk_bf16_f32 v81, v82, v83
	v_cvt_pk_bf16_f32 v82, v84, v85
	v_cvt_pk_bf16_f32 v83, v86, v87
	v_cvt_pk_bf16_f32 v84, v88, v89
	v_cvt_pk_bf16_f32 v85, v90, v91
	v_cvt_pk_bf16_f32 v86, v92, v93
	v_cvt_pk_bf16_f32 v87, v94, v95
	ds_write_b16 v180, v80 offset:4608
	ds_write_b16_d16_hi v180, v80 offset:4752
	ds_write_b16 v180, v81 offset:4896
	ds_write_b16_d16_hi v180, v81 offset:5040
	ds_write_b16 v180, v82 offset:5760
	ds_write_b16_d16_hi v180, v82 offset:5904
	ds_write_b16 v180, v83 offset:6048
	ds_write_b16_d16_hi v180, v83 offset:6192
	ds_write_b16 v180, v84 offset:6912
	ds_write_b16_d16_hi v180, v84 offset:7056
	ds_write_b16 v180, v85 offset:7200
	ds_write_b16_d16_hi v180, v85 offset:7344
	ds_write_b16 v180, v86 offset:8064
	ds_write_b16_d16_hi v180, v86 offset:8208
	ds_write_b16 v180, v87 offset:8352
	ds_write_b16_d16_hi v180, v87 offset:8496
	v_cvt_pk_bf16_f32 v96, v96, v97
	v_cvt_pk_bf16_f32 v97, v98, v99
	v_cvt_pk_bf16_f32 v98, v100, v101
	v_cvt_pk_bf16_f32 v99, v102, v103
	v_cvt_pk_bf16_f32 v100, v104, v105
	v_cvt_pk_bf16_f32 v101, v106, v107
	v_cvt_pk_bf16_f32 v102, v108, v109
	v_cvt_pk_bf16_f32 v103, v110, v111
	ds_write_b16 v180, v96 offset:64
	ds_write_b16_d16_hi v180, v96 offset:208
	ds_write_b16 v180, v97 offset:352
	ds_write_b16_d16_hi v180, v97 offset:496
	ds_write_b16 v180, v98 offset:1216
	ds_write_b16_d16_hi v180, v98 offset:1360
	ds_write_b16 v180, v99 offset:1504
	ds_write_b16_d16_hi v180, v99 offset:1648
	ds_write_b16 v180, v100 offset:2368
	ds_write_b16_d16_hi v180, v100 offset:2512
	ds_write_b16 v180, v101 offset:2656
	ds_write_b16_d16_hi v180, v101 offset:2800
	ds_write_b16 v180, v102 offset:3520
	ds_write_b16_d16_hi v180, v102 offset:3664
	ds_write_b16 v180, v103 offset:3808
	ds_write_b16_d16_hi v180, v103 offset:3952
	v_cvt_pk_bf16_f32 v112, v112, v113
	v_cvt_pk_bf16_f32 v113, v114, v115
	v_cvt_pk_bf16_f32 v114, v116, v117
	v_cvt_pk_bf16_f32 v115, v118, v119
	v_cvt_pk_bf16_f32 v116, v120, v121
	v_cvt_pk_bf16_f32 v117, v122, v123
	v_cvt_pk_bf16_f32 v118, v124, v125
	v_cvt_pk_bf16_f32 v119, v126, v127
	ds_write_b16 v180, v112 offset:4672
	ds_write_b16_d16_hi v180, v112 offset:4816
	ds_write_b16 v180, v113 offset:4960
	ds_write_b16_d16_hi v180, v113 offset:5104
	ds_write_b16 v180, v114 offset:5824
	ds_write_b16_d16_hi v180, v114 offset:5968
	ds_write_b16 v180, v115 offset:6112
	ds_write_b16_d16_hi v180, v115 offset:6256
	ds_write_b16 v180, v116 offset:6976
	ds_write_b16_d16_hi v180, v116 offset:7120
	ds_write_b16 v180, v117 offset:7264
	ds_write_b16_d16_hi v180, v117 offset:7408
	ds_write_b16 v180, v118 offset:8128
	ds_write_b16_d16_hi v180, v118 offset:8272
	ds_write_b16 v180, v119 offset:8416
	ds_write_b16_d16_hi v180, v119 offset:8560
	s_waitcnt lgkmcnt(0)
	ds_read_b128 v[64:67], v198 offset:0
	ds_read_b128 v[68:71], v198 offset:1152
	ds_read_b128 v[72:75], v198 offset:2304
	ds_read_b128 v[76:79], v198 offset:3456
	ds_read_b128 v[80:83], v198 offset:4608
	ds_read_b128 v[84:87], v198 offset:5760
	ds_read_b128 v[88:91], v198 offset:6912
	ds_read_b128 v[92:95], v198 offset:8064
	s_waitcnt lgkmcnt(7)
	global_store_dwordx4 v199, v[64:67], s[38:39]
	s_add_u32 s38, s38, 0x8000
	s_addc_u32 s39, s39, 0
	s_waitcnt lgkmcnt(6)
	global_store_dwordx4 v199, v[68:71], s[38:39]
	s_add_u32 s38, s38, 0x8000
	s_addc_u32 s39, s39, 0
	s_waitcnt lgkmcnt(5)
	global_store_dwordx4 v199, v[72:75], s[38:39]
	s_add_u32 s38, s38, 0x8000
	s_addc_u32 s39, s39, 0
	s_waitcnt lgkmcnt(4)
	global_store_dwordx4 v199, v[76:79], s[38:39]
	s_add_u32 s38, s38, 0x8000
	s_addc_u32 s39, s39, 0
	s_waitcnt lgkmcnt(3)
	global_store_dwordx4 v199, v[80:83], s[38:39]
	s_add_u32 s38, s38, 0x8000
	s_addc_u32 s39, s39, 0
	s_waitcnt lgkmcnt(2)
	global_store_dwordx4 v199, v[84:87], s[38:39]
	s_add_u32 s38, s38, 0x8000
	s_addc_u32 s39, s39, 0
	s_waitcnt lgkmcnt(1)
	global_store_dwordx4 v199, v[88:91], s[38:39]
	s_add_u32 s38, s38, 0x8000
	s_addc_u32 s39, s39, 0
	s_waitcnt lgkmcnt(0)
	global_store_dwordx4 v199, v[92:95], s[38:39]

.LBB0_724:
	s_lshl_b32 s4, s86, 3
	s_and_b32 s16, s4, 56
	s_bfe_u32 s4, s86, 0x30003
	s_or_b32 s24, s16, s4
	s_lshl_b32 s33, s86, 2
	s_lshr_b32 s25, s86, 3
	s_and_b32 s48, s33, 0xffffff00
	s_lshl_b32 s4, s24, 19
	s_add_u32 s6, s21, s4
	s_addc_u32 s7, s47, 0
	s_ashr_i32 s49, s48, 31
	s_lshl_b64 s[4:5], s[48:49], 11
	s_add_u32 s26, s60, s4
	v_readfirstlane_b32 s4, v176
	s_addc_u32 s27, s61, s5
	s_ashr_i32 s28, s4, 6
	s_lshl_b32 s4, s28, 5
	s_ashr_i32 s5, s4, 31
	s_lshl_b64 s[4:5], s[4:5], 11
	s_add_u32 s6, s6, s4
	s_addc_u32 s7, s7, s5
	s_add_u32 s4, s26, s4
	s_addc_u32 s5, s27, s5
	s_lshl_b32 s26, s28, 12
	s_add_i32 s27, s26, 0x8000
	s_and_b32 s81, s24, 7
	s_lshl_b32 s81, s81, 8
	s_and_b32 s82, s48, 0x300
	s_lshl_b32 s82, s82, 1
	s_add_u32 s81, s81, s82
	s_and_b32 s81, s81, 0x7ff
	s_add_u32 s6, s6, s81
	s_addc_u32 s7, s7, 0
	s_add_u32 s4, s4, s81
	s_addc_u32 s5, s5, 0
	s_cmp_eq_u32 s80, 1
	s_cbranch_scc1 .Lpf_skip_L1
	s_add_u32 s28, s6, 0x4000
	s_barrier
	s_mov_b32 m0, s26
	global_load_lds_dwordx4 v177, s[6:7]
	s_addc_u32 s29, s7, 0
	s_or_b32 s30, s26, 0x400
	s_mov_b32 m0, s30
	global_load_lds_dwordx4 v185, s[28:29]
	s_add_u32 s28, s6, 0x8000
	s_addc_u32 s29, s7, 0
	s_or_b32 s30, s26, 0x800
	s_mov_b32 m0, s30
	global_load_lds_dwordx4 v177, s[28:29]
	s_add_u32 s28, s6, 0xc000
	s_addc_u32 s29, s7, 0
	s_or_b32 s30, s26, 0xc00
	s_mov_b32 m0, s30
	global_load_lds_dwordx4 v185, s[28:29]
	s_add_u32 s28, s4, 0x4000
	s_mov_b32 m0, s27
	global_load_lds_dwordx4 v177, s[4:5]
	s_addc_u32 s29, s5, 0
	s_add_i32 s27, s26, 0x8400
	s_mov_b32 m0, s27
	global_load_lds_dwordx4 v185, s[28:29]
	s_add_u32 s28, s4, 0x8000
	s_addc_u32 s29, s5, 0
	s_add_i32 s27, s26, 0x8800
	s_mov_b32 m0, s27
	global_load_lds_dwordx4 v177, s[28:29]
	s_add_u32 s28, s4, 0xc000
	s_addc_u32 s29, s5, 0
	s_add_i32 s27, s26, 0x8c00
	s_mov_b32 m0, s27
	global_load_lds_dwordx4 v185, s[28:29]

.Lpe_notv_L1:
	s_cmp_ge_u32 s25, 9
	s_cbranch_scc1 .Lpe_gates_L1
	s_lshr_b32 s34, s25, 1
	s_cmp_ge_u32 s25, 6
	s_cselect_b32 s35, 1, 0
	s_sub_u32 s34, s34, s35
	s_lshl_b32 s35, s98, 2
	s_add_u32 s35, s35, s34
	s_lshl_b32 s35, s35, 8
	v_readlane_b32 s82, v254, 14
	v_readlane_b32 s83, v254, 15
	s_add_u32 s82, s82, s35
	s_addc_u32 s83, s83, 0
	global_load_dwordx4 v[198:201], v146, s[82:83] offset:0
	global_load_dwordx4 v[202:205], v146, s[82:83] offset:32
	global_load_dwordx4 v[206:209], v146, s[82:83] offset:64
	global_load_dwordx4 v[210:213], v146, s[82:83] offset:96
	global_load_dwordx4 v[214:217], v146, s[82:83] offset:128
	global_load_dwordx4 v[218:221], v146, s[82:83] offset:160
	global_load_dwordx4 v[222:225], v146, s[82:83] offset:192
	global_load_dwordx4 v[226:229], v146, s[82:83] offset:224
	s_and_b32 s35, s34, 1
	s_cmp_eq_u32 s35, 0
	s_cselect_b32 s36, 0x3e000000, 1.0
	s_and_b32 s35, s29, 0x7ff
	s_lshl_b32 s35, s35, 7
	s_add_u32 s96, s72, 0x1ada0000
	s_addc_u32 s97, s73, 0
	s_add_u32 s96, s96, s35
	s_addc_u32 s97, s97, 0
	s_add_u32 s100, s96, 0x40000
	s_addc_u32 s101, s97, 0
	s_cmp_ge_u32 s34, 2
	s_cselect_b32 s37, 1, 0
	s_waitcnt vmcnt(8)
	v_lshlrev_b32_e32 v180, 7, v197
	v_add_u32_e32 v180, v180, v146
	v_mov_b32_e32 v197, 0x358637bd
	v_pk_add_f32 v[128:129], v[128:129], v[130:131]
	v_pk_add_f32 v[132:133], v[132:133], v[134:135]
	v_pk_add_f32 v[136:137], v[136:137], v[138:139]
	v_pk_add_f32 v[140:141], v[140:141], v[142:143]
	v_pk_add_f32 v[164:165], v[164:165], v[166:167]
	v_pk_add_f32 v[168:169], v[168:169], v[170:171]
	v_pk_add_f32 v[246:247], v[246:247], v[248:249]
	v_pk_add_f32 v[250:251], v[250:251], v[252:253]
	v_pk_add_f32 v[128:129], v[128:129], v[132:133]
	v_pk_add_f32 v[136:137], v[136:137], v[140:141]
	v_pk_add_f32 v[164:165], v[164:165], v[168:169]
	v_pk_add_f32 v[246:247], v[246:247], v[250:251]
	v_add_f32_e32 v128, v128, v129
	v_add_f32_e32 v136, v136, v137
	v_add_f32_e32 v164, v164, v165
	v_add_f32_e32 v246, v246, v247
	v_fmamk_f32 v128, v128, 0x3a800000, v197
	v_fmamk_f32 v136, v136, 0x3a800000, v197
	v_fmamk_f32 v164, v164, 0x3a800000, v197
	v_fmamk_f32 v246, v246, 0x3a800000, v197
	v_rsq_f32_e32 v172, v128
	v_rsq_f32_e32 v173, v136
	v_rsq_f32_e32 v174, v164
	v_rsq_f32_e32 v175, v246
	s_nop 0
	s_add_u32 s76, s99, s90
	s_cmp_lt_u32 s76, 0x440
	s_cselect_b32 s80, 1, 0
	s_cselect_b32 s83, 0x200000, 0
	s_lshl_b32 s76, s24, 19
	s_lshl_b32 s77, s26, 16
	s_add_u32 s76, s76, s77
	s_and_b32 s77, s24, 7
	s_lshl_b32 s77, s77, 8
	s_and_b32 s82, s25, 3
	s_lshl_b32 s82, s82, 9
	s_add_u32 s77, s77, s82
	s_and_b32 s77, s77, 0x7ff
	s_add_u32 s76, s76, s77
	s_add_u32 s78, s72, 0xa120000
	s_addc_u32 s79, s73, 0
	s_add_u32 s78, s78, s76
	s_addc_u32 s79, s79, 0
	s_lshl_b32 s76, s25, 19
	s_add_u32 s76, s76, s83
	s_add_u32 s76, s76, s77
	s_lshl_b32 s77, s26, 16
	s_add_u32 s76, s76, s77
	s_add_u32 s82, s72, 0x880000
	s_addc_u32 s83, s73, 0
	s_add_u32 s82, s82, s76
	s_addc_u32 s83, s83, 0
	s_lshl_b32 s76, s26, 12
	s_mov_b32 m0, s76
	s_nop 0
	global_load_lds_dwordx4 v177, s[78:79]
	s_add_u32 s78, s78, 0x4000
	s_addc_u32 s79, s79, 0
	s_add_u32 s76, s76, 0x400
	s_mov_b32 m0, s76
	s_nop 0
	global_load_lds_dwordx4 v185, s[78:79]
	s_add_u32 s78, s78, 0x4000
	s_addc_u32 s79, s79, 0
	s_add_u32 s76, s76, 0x400
	s_mov_b32 m0, s76
	s_nop 0
	global_load_lds_dwordx4 v177, s[78:79]
	s_add_u32 s78, s78, 0x4000
	s_addc_u32 s79, s79, 0
	s_add_u32 s76, s76, 0x400
	s_mov_b32 m0, s76
	s_nop 0
	global_load_lds_dwordx4 v185, s[78:79]
	s_add_u32 s78, s78, 0x4000
	s_addc_u32 s79, s79, 0
	s_add_u32 s76, s76, 0x400
	s_add_u32 s76, s76, 0x7000
	s_mov_b32 m0, s76
	s_nop 0
	global_load_lds_dwordx4 v177, s[82:83]
	s_add_u32 s82, s82, 0x4000
	s_addc_u32 s83, s83, 0
	s_add_u32 s76, s76, 0x400
	s_mov_b32 m0, s76
	s_nop 0
	global_load_lds_dwordx4 v185, s[82:83]
	s_add_u32 s82, s82, 0x4000
	s_addc_u32 s83, s83, 0
	s_add_u32 s76, s76, 0x400
	s_mov_b32 m0, s76
	s_nop 0
	global_load_lds_dwordx4 v177, s[82:83]
	s_add_u32 s82, s82, 0x4000
	s_addc_u32 s83, s83, 0
	s_add_u32 s76, s76, 0x400
	s_mov_b32 m0, s76
	s_nop 0
	global_load_lds_dwordx4 v185, s[82:83]
	s_add_u32 s82, s82, 0x4000
	s_addc_u32 s83, s83, 0
	s_add_u32 s76, s76, 0x400
	s_cmp_eq_u32 s37, 0
	s_cbranch_scc1 .Lpe_norope_ld_L1
	global_load_dwordx4 v[230:233], v180, s[96:97] offset:0
	global_load_dwordx4 v[234:237], v180, s[96:97] offset:32
	global_load_dwordx4 v[238:241], v180, s[96:97] offset:64
	global_load_dwordx4 v[242:245], v180, s[96:97] offset:96
	global_load_dwordx4 v[148:151], v180, s[100:101] offset:0
	global_load_dwordx4 v[152:155], v180, s[100:101] offset:32
	global_load_dwordx4 v[156:159], v180, s[100:101] offset:64
	global_load_dwordx4 v[160:163], v180, s[100:101] offset:96

.Lpe_gates_L1:
	s_lshl_b32 s35, s98, 11
	s_add_u32 s35, s35, s30
	s_sub_u32 s35, s35, 0x900
	s_lshl_b32 s35, s35, 2
	v_readlane_b32 s82, v254, 12
	v_readlane_b32 s83, v254, 13
	s_add_u32 s82, s82, s35
	s_addc_u32 s83, s83, 0
	global_load_dwordx4 v[198:201], v146, s[82:83] offset:0
	global_load_dwordx4 v[202:205], v146, s[82:83] offset:32
	global_load_dwordx4 v[206:209], v146, s[82:83] offset:64
	global_load_dwordx4 v[210:213], v146, s[82:83] offset:96
	global_load_dwordx4 v[214:217], v146, s[82:83] offset:128
	global_load_dwordx4 v[218:221], v146, s[82:83] offset:160
	global_load_dwordx4 v[222:225], v146, s[82:83] offset:192
	global_load_dwordx4 v[226:229], v146, s[82:83] offset:224
	s_waitcnt vmcnt(8)
	v_mov_b32_e32 v197, 0x358637bd
	v_pk_add_f32 v[128:129], v[128:129], v[130:131]
	v_pk_add_f32 v[132:133], v[132:133], v[134:135]
	v_pk_add_f32 v[136:137], v[136:137], v[138:139]
	v_pk_add_f32 v[140:141], v[140:141], v[142:143]
	v_pk_add_f32 v[164:165], v[164:165], v[166:167]
	v_pk_add_f32 v[168:169], v[168:169], v[170:171]
	v_pk_add_f32 v[246:247], v[246:247], v[248:249]
	v_pk_add_f32 v[250:251], v[250:251], v[252:253]
	v_pk_add_f32 v[128:129], v[128:129], v[132:133]
	v_pk_add_f32 v[136:137], v[136:137], v[140:141]
	v_pk_add_f32 v[164:165], v[164:165], v[168:169]
	v_pk_add_f32 v[246:247], v[246:247], v[250:251]
	v_add_f32_e32 v128, v128, v129
	v_add_f32_e32 v136, v136, v137
	v_add_f32_e32 v164, v164, v165
	v_add_f32_e32 v246, v246, v247
	v_fmamk_f32 v128, v128, 0x3a800000, v197
	v_fmamk_f32 v136, v136, 0x3a800000, v197
	v_fmamk_f32 v164, v164, 0x3a800000, v197
	v_fmamk_f32 v246, v246, 0x3a800000, v197
	v_rsq_f32_e32 v172, v128
	v_rsq_f32_e32 v173, v136
	v_rsq_f32_e32 v174, v164
	v_rsq_f32_e32 v175, v246
	s_nop 0
	s_add_u32 s76, s99, s90
	s_cmp_lt_u32 s76, 0x440
	s_cselect_b32 s80, 1, 0
	s_cselect_b32 s83, 0x200000, 0
	s_lshl_b32 s76, s24, 19
	s_lshl_b32 s77, s26, 16
	s_add_u32 s76, s76, s77
	s_and_b32 s77, s24, 7
	s_lshl_b32 s77, s77, 8
	s_and_b32 s82, s25, 3
	s_lshl_b32 s82, s82, 9
	s_add_u32 s77, s77, s82
	s_and_b32 s77, s77, 0x7ff
	s_add_u32 s76, s76, s77
	s_add_u32 s78, s72, 0xa120000
	s_addc_u32 s79, s73, 0
	s_add_u32 s78, s78, s76
	s_addc_u32 s79, s79, 0
	s_lshl_b32 s76, s25, 19
	s_add_u32 s76, s76, s83
	s_add_u32 s76, s76, s77
	s_lshl_b32 s77, s26, 16
	s_add_u32 s76, s76, s77
	s_add_u32 s82, s72, 0x880000
	s_addc_u32 s83, s73, 0
	s_add_u32 s82, s82, s76
	s_addc_u32 s83, s83, 0
	s_lshl_b32 s76, s26, 12
	s_mov_b32 m0, s76
	s_nop 0
	global_load_lds_dwordx4 v177, s[78:79]
	s_add_u32 s78, s78, 0x4000
	s_addc_u32 s79, s79, 0
	s_add_u32 s76, s76, 0x400
	s_mov_b32 m0, s76
	s_nop 0
	global_load_lds_dwordx4 v185, s[78:79]
	s_add_u32 s78, s78, 0x4000
	s_addc_u32 s79, s79, 0
	s_add_u32 s76, s76, 0x400
	s_mov_b32 m0, s76
	s_nop 0
	global_load_lds_dwordx4 v177, s[78:79]
	s_add_u32 s78, s78, 0x4000
	s_addc_u32 s79, s79, 0
	s_add_u32 s76, s76, 0x400
	s_mov_b32 m0, s76
	s_nop 0
	global_load_lds_dwordx4 v185, s[78:79]
	s_add_u32 s78, s78, 0x4000
	s_addc_u32 s79, s79, 0
	s_add_u32 s76, s76, 0x400
	s_add_u32 s76, s76, 0x7000
	s_mov_b32 m0, s76
	s_nop 0
	global_load_lds_dwordx4 v177, s[82:83]
	s_add_u32 s82, s82, 0x4000
	s_addc_u32 s83, s83, 0
	s_add_u32 s76, s76, 0x400
	s_mov_b32 m0, s76
	s_nop 0
	global_load_lds_dwordx4 v185, s[82:83]
	s_add_u32 s82, s82, 0x4000
	s_addc_u32 s83, s83, 0
	s_add_u32 s76, s76, 0x400
	s_mov_b32 m0, s76
	s_nop 0
	global_load_lds_dwordx4 v177, s[82:83]
	s_add_u32 s82, s82, 0x4000
	s_addc_u32 s83, s83, 0
	s_add_u32 s76, s76, 0x400
	s_mov_b32 m0, s76
	s_nop 0
	global_load_lds_dwordx4 v185, s[82:83]
	s_add_u32 s82, s82, 0x4000
	s_addc_u32 s83, s83, 0
	s_add_u32 s76, s76, 0x400
	v_mul_f32_e32 v172, 0xbfb8aa3b, v172
	v_mul_f32_e32 v173, 0xbfb8aa3b, v173
	v_mul_f32_e32 v174, 0xbfb8aa3b, v174
	v_mul_f32_e32 v175, 0xbfb8aa3b, v175
	s_waitcnt vmcnt(8)
	v_mul_f32_e32 v198, 0xbfb8aa3b, v198
	v_mul_f32_e32 v199, 0xbfb8aa3b, v199
	v_mul_f32_e32 v200, 0xbfb8aa3b, v200
	v_mul_f32_e32 v201, 0xbfb8aa3b, v201
	v_mul_f32_e32 v202, 0xbfb8aa3b, v202
	v_mul_f32_e32 v203, 0xbfb8aa3b, v203
	v_mul_f32_e32 v204, 0xbfb8aa3b, v204
	v_mul_f32_e32 v205, 0xbfb8aa3b, v205
	v_mul_f32_e32 v206, 0xbfb8aa3b, v206
	v_mul_f32_e32 v207, 0xbfb8aa3b, v207
	v_mul_f32_e32 v208, 0xbfb8aa3b, v208
	v_mul_f32_e32 v209, 0xbfb8aa3b, v209
	v_mul_f32_e32 v210, 0xbfb8aa3b, v210
	v_mul_f32_e32 v211, 0xbfb8aa3b, v211
	v_mul_f32_e32 v212, 0xbfb8aa3b, v212
	v_mul_f32_e32 v213, 0xbfb8aa3b, v213
	v_mul_f32_e32 v214, 0xbfb8aa3b, v214
	v_mul_f32_e32 v215, 0xbfb8aa3b, v215
	v_mul_f32_e32 v216, 0xbfb8aa3b, v216
	v_mul_f32_e32 v217, 0xbfb8aa3b, v217
	v_mul_f32_e32 v218, 0xbfb8aa3b, v218
	v_mul_f32_e32 v219, 0xbfb8aa3b, v219
	v_mul_f32_e32 v220, 0xbfb8aa3b, v220
	v_mul_f32_e32 v221, 0xbfb8aa3b, v221
	v_mul_f32_e32 v222, 0xbfb8aa3b, v222
	v_mul_f32_e32 v223, 0xbfb8aa3b, v223
	v_mul_f32_e32 v224, 0xbfb8aa3b, v224
	v_mul_f32_e32 v225, 0xbfb8aa3b, v225
	v_mul_f32_e32 v226, 0xbfb8aa3b, v226
	v_mul_f32_e32 v227, 0xbfb8aa3b, v227
	v_mul_f32_e32 v228, 0xbfb8aa3b, v228
	v_mul_f32_e32 v229, 0xbfb8aa3b, v229
	v_pk_fma_f32 v[0:1], v[0:1], v[172:173], v[198:199] op_sel_hi:[1,0,1]
	v_pk_fma_f32 v[2:3], v[2:3], v[172:173], v[200:201] op_sel_hi:[1,0,1]
	v_pk_fma_f32 v[4:5], v[4:5], v[172:173], v[202:203] op_sel_hi:[1,0,1]
	v_pk_fma_f32 v[6:7], v[6:7], v[172:173], v[204:205] op_sel_hi:[1,0,1]
	v_pk_fma_f32 v[8:9], v[8:9], v[172:173], v[206:207] op_sel_hi:[1,0,1]
	v_pk_fma_f32 v[10:11], v[10:11], v[172:173], v[208:209] op_sel_hi:[1,0,1]
	v_pk_fma_f32 v[12:13], v[12:13], v[172:173], v[210:211] op_sel_hi:[1,0,1]
	v_pk_fma_f32 v[14:15], v[14:15], v[172:173], v[212:213] op_sel_hi:[1,0,1]
	v_pk_fma_f32 v[16:17], v[16:17], v[172:173], v[214:215] op_sel_hi:[1,0,1]
	v_pk_fma_f32 v[18:19], v[18:19], v[172:173], v[216:217] op_sel_hi:[1,0,1]
	v_pk_fma_f32 v[20:21], v[20:21], v[172:173], v[218:219] op_sel_hi:[1,0,1]
	v_pk_fma_f32 v[22:23], v[22:23], v[172:173], v[220:221] op_sel_hi:[1,0,1]
	v_pk_fma_f32 v[24:25], v[24:25], v[172:173], v[222:223] op_sel_hi:[1,0,1]
	v_pk_fma_f32 v[26:27], v[26:27], v[172:173], v[224:225] op_sel_hi:[1,0,1]
	v_pk_fma_f32 v[28:29], v[28:29], v[172:173], v[226:227] op_sel_hi:[1,0,1]
	v_pk_fma_f32 v[30:31], v[30:31], v[172:173], v[228:229] op_sel_hi:[1,0,1]
	v_exp_f32_e32 v0, v0
	v_exp_f32_e32 v1, v1
	v_exp_f32_e32 v2, v2
	v_exp_f32_e32 v3, v3
	v_exp_f32_e32 v4, v4
	v_exp_f32_e32 v5, v5
	v_exp_f32_e32 v6, v6
	v_exp_f32_e32 v7, v7
	v_exp_f32_e32 v8, v8
	v_exp_f32_e32 v9, v9
	v_exp_f32_e32 v10, v10
	v_exp_f32_e32 v11, v11
	v_exp_f32_e32 v12, v12
	v_exp_f32_e32 v13, v13
	v_exp_f32_e32 v14, v14
	v_exp_f32_e32 v15, v15
	v_exp_f32_e32 v16, v16
	v_exp_f32_e32 v17, v17
	v_exp_f32_e32 v18, v18
	v_exp_f32_e32 v19, v19
	v_exp_f32_e32 v20, v20
	v_exp_f32_e32 v21, v21
	v_exp_f32_e32 v22, v22
	v_exp_f32_e32 v23, v23
	v_exp_f32_e32 v24, v24
	v_exp_f32_e32 v25, v25
	v_exp_f32_e32 v26, v26
	v_exp_f32_e32 v27, v27
	v_exp_f32_e32 v28, v28
	v_exp_f32_e32 v29, v29
	v_exp_f32_e32 v30, v30
	v_exp_f32_e32 v31, v31
	v_pk_add_f32 v[0:1], v[0:1], 1.0 op_sel_hi:[1,0]
	v_pk_add_f32 v[2:3], v[2:3], 1.0 op_sel_hi:[1,0]
	v_pk_add_f32 v[4:5], v[4:5], 1.0 op_sel_hi:[1,0]
	v_pk_add_f32 v[6:7], v[6:7], 1.0 op_sel_hi:[1,0]
	v_pk_add_f32 v[8:9], v[8:9], 1.0 op_sel_hi:[1,0]
	v_pk_add_f32 v[10:11], v[10:11], 1.0 op_sel_hi:[1,0]
	v_pk_add_f32 v[12:13], v[12:13], 1.0 op_sel_hi:[1,0]
	v_pk_add_f32 v[14:15], v[14:15], 1.0 op_sel_hi:[1,0]
	v_pk_add_f32 v[16:17], v[16:17], 1.0 op_sel_hi:[1,0]
	v_pk_add_f32 v[18:19], v[18:19], 1.0 op_sel_hi:[1,0]
	v_pk_add_f32 v[20:21], v[20:21], 1.0 op_sel_hi:[1,0]
	v_pk_add_f32 v[22:23], v[22:23], 1.0 op_sel_hi:[1,0]
	v_pk_add_f32 v[24:25], v[24:25], 1.0 op_sel_hi:[1,0]
	v_pk_add_f32 v[26:27], v[26:27], 1.0 op_sel_hi:[1,0]
	v_pk_add_f32 v[28:29], v[28:29], 1.0 op_sel_hi:[1,0]
	v_pk_add_f32 v[30:31], v[30:31], 1.0 op_sel_hi:[1,0]
	v_rcp_f32_e32 v0, v0
	v_rcp_f32_e32 v1, v1
	v_rcp_f32_e32 v2, v2
	v_rcp_f32_e32 v3, v3
	v_rcp_f32_e32 v4, v4
	v_rcp_f32_e32 v5, v5
	v_rcp_f32_e32 v6, v6
	v_rcp_f32_e32 v7, v7
	v_rcp_f32_e32 v8, v8
	v_rcp_f32_e32 v9, v9
	v_rcp_f32_e32 v10, v10
	v_rcp_f32_e32 v11, v11
	v_rcp_f32_e32 v12, v12
	v_rcp_f32_e32 v13, v13
	v_rcp_f32_e32 v14, v14
	v_rcp_f32_e32 v15, v15
	v_rcp_f32_e32 v16, v16
	v_rcp_f32_e32 v17, v17
	v_rcp_f32_e32 v18, v18
	v_rcp_f32_e32 v19, v19
	v_rcp_f32_e32 v20, v20
	v_rcp_f32_e32 v21, v21
	v_rcp_f32_e32 v22, v22
	v_rcp_f32_e32 v23, v23
	v_rcp_f32_e32 v24, v24
	v_rcp_f32_e32 v25, v25
	v_rcp_f32_e32 v26, v26
	v_rcp_f32_e32 v27, v27
	v_rcp_f32_e32 v28, v28
	v_rcp_f32_e32 v29, v29
	v_rcp_f32_e32 v30, v30
	v_rcp_f32_e32 v31, v31
	s_nop 0
	v_cvt_pk_bf16_f32 v0, v0, v1
	v_cvt_pk_bf16_f32 v1, v2, v3
	v_cvt_pk_bf16_f32 v2, v4, v5
	v_cvt_pk_bf16_f32 v3, v6, v7
	v_cvt_pk_bf16_f32 v4, v8, v9
	v_cvt_pk_bf16_f32 v5, v10, v11
	v_cvt_pk_bf16_f32 v6, v12, v13
	v_cvt_pk_bf16_f32 v7, v14, v15
	v_cvt_pk_bf16_f32 v16, v16, v17
	v_cvt_pk_bf16_f32 v17, v18, v19
	v_cvt_pk_bf16_f32 v18, v20, v21
	v_cvt_pk_bf16_f32 v19, v22, v23
	v_cvt_pk_bf16_f32 v20, v24, v25
	v_cvt_pk_bf16_f32 v21, v26, v27
	v_cvt_pk_bf16_f32 v22, v28, v29
	v_cvt_pk_bf16_f32 v23, v30, v31
	v_permlane32_swap_b32_e32 v0, v2
	v_permlane32_swap_b32_e32 v1, v3
	v_permlane32_swap_b32_e32 v4, v6
	v_permlane32_swap_b32_e32 v5, v7
	v_permlane32_swap_b32_e32 v16, v18
	v_permlane32_swap_b32_e32 v17, v19
	v_permlane32_swap_b32_e32 v20, v22
	v_permlane32_swap_b32_e32 v21, v23
	global_store_dwordx4 v181, v[0:3], s[74:75] offset:0
	global_store_dwordx4 v181, v[4:7], s[74:75] offset:32
	global_store_dwordx4 v181, v[16:19], s[74:75] offset:64
	global_store_dwordx4 v181, v[20:23], s[74:75] offset:96
	s_add_u32 s74, s74, 0x44000
	s_addc_u32 s75, s75, 0
	v_pk_fma_f32 v[32:33], v[32:33], v[172:173], v[198:199] op_sel:[0,1,0] op_sel_hi:[1,1,1]
	v_pk_fma_f32 v[34:35], v[34:35], v[172:173], v[200:201] op_sel:[0,1,0] op_sel_hi:[1,1,1]
	v_pk_fma_f32 v[36:37], v[36:37], v[172:173], v[202:203] op_sel:[0,1,0] op_sel_hi:[1,1,1]
	v_pk_fma_f32 v[38:39], v[38:39], v[172:173], v[204:205] op_sel:[0,1,0] op_sel_hi:[1,1,1]
	v_pk_fma_f32 v[40:41], v[40:41], v[172:173], v[206:207] op_sel:[0,1,0] op_sel_hi:[1,1,1]
	v_pk_fma_f32 v[42:43], v[42:43], v[172:173], v[208:209] op_sel:[0,1,0] op_sel_hi:[1,1,1]
	v_pk_fma_f32 v[44:45], v[44:45], v[172:173], v[210:211] op_sel:[0,1,0] op_sel_hi:[1,1,1]
	v_pk_fma_f32 v[46:47], v[46:47], v[172:173], v[212:213] op_sel:[0,1,0] op_sel_hi:[1,1,1]
	v_pk_fma_f32 v[48:49], v[48:49], v[172:173], v[214:215] op_sel:[0,1,0] op_sel_hi:[1,1,1]
	v_pk_fma_f32 v[50:51], v[50:51], v[172:173], v[216:217] op_sel:[0,1,0] op_sel_hi:[1,1,1]
	v_pk_fma_f32 v[52:53], v[52:53], v[172:173], v[218:219] op_sel:[0,1,0] op_sel_hi:[1,1,1]
	v_pk_fma_f32 v[54:55], v[54:55], v[172:173], v[220:221] op_sel:[0,1,0] op_sel_hi:[1,1,1]
	v_pk_fma_f32 v[56:57], v[56:57], v[172:173], v[222:223] op_sel:[0,1,0] op_sel_hi:[1,1,1]
	v_pk_fma_f32 v[58:59], v[58:59], v[172:173], v[224:225] op_sel:[0,1,0] op_sel_hi:[1,1,1]
	v_pk_fma_f32 v[60:61], v[60:61], v[172:173], v[226:227] op_sel:[0,1,0] op_sel_hi:[1,1,1]
	v_pk_fma_f32 v[62:63], v[62:63], v[172:173], v[228:229] op_sel:[0,1,0] op_sel_hi:[1,1,1]
	v_exp_f32_e32 v32, v32
	v_exp_f32_e32 v33, v33
	v_exp_f32_e32 v34, v34
	v_exp_f32_e32 v35, v35
	v_exp_f32_e32 v36, v36
	v_exp_f32_e32 v37, v37
	v_exp_f32_e32 v38, v38
	v_exp_f32_e32 v39, v39
	v_exp_f32_e32 v40, v40
	v_exp_f32_e32 v41, v41
	v_exp_f32_e32 v42, v42
	v_exp_f32_e32 v43, v43
	v_exp_f32_e32 v44, v44
	v_exp_f32_e32 v45, v45
	v_exp_f32_e32 v46, v46
	v_exp_f32_e32 v47, v47
	v_exp_f32_e32 v48, v48
	v_exp_f32_e32 v49, v49
	v_exp_f32_e32 v50, v50
	v_exp_f32_e32 v51, v51
	v_exp_f32_e32 v52, v52
	v_exp_f32_e32 v53, v53
	v_exp_f32_e32 v54, v54
	v_exp_f32_e32 v55, v55
	v_exp_f32_e32 v56, v56
	v_exp_f32_e32 v57, v57
	v_exp_f32_e32 v58, v58
	v_exp_f32_e32 v59, v59
	v_exp_f32_e32 v60, v60
	v_exp_f32_e32 v61, v61
	v_exp_f32_e32 v62, v62
	v_exp_f32_e32 v63, v63
	v_pk_add_f32 v[32:33], v[32:33], 1.0 op_sel_hi:[1,0]
	v_pk_add_f32 v[34:35], v[34:35], 1.0 op_sel_hi:[1,0]
	v_pk_add_f32 v[36:37], v[36:37], 1.0 op_sel_hi:[1,0]
	v_pk_add_f32 v[38:39], v[38:39], 1.0 op_sel_hi:[1,0]
	v_pk_add_f32 v[40:41], v[40:41], 1.0 op_sel_hi:[1,0]
	v_pk_add_f32 v[42:43], v[42:43], 1.0 op_sel_hi:[1,0]
	v_pk_add_f32 v[44:45], v[44:45], 1.0 op_sel_hi:[1,0]
	v_pk_add_f32 v[46:47], v[46:47], 1.0 op_sel_hi:[1,0]
	v_pk_add_f32 v[48:49], v[48:49], 1.0 op_sel_hi:[1,0]
	v_pk_add_f32 v[50:51], v[50:51], 1.0 op_sel_hi:[1,0]
	v_pk_add_f32 v[52:53], v[52:53], 1.0 op_sel_hi:[1,0]
	v_pk_add_f32 v[54:55], v[54:55], 1.0 op_sel_hi:[1,0]
	v_pk_add_f32 v[56:57], v[56:57], 1.0 op_sel_hi:[1,0]
	v_pk_add_f32 v[58:59], v[58:59], 1.0 op_sel_hi:[1,0]
	v_pk_add_f32 v[60:61], v[60:61], 1.0 op_sel_hi:[1,0]
	v_pk_add_f32 v[62:63], v[62:63], 1.0 op_sel_hi:[1,0]
	v_rcp_f32_e32 v32, v32
	v_rcp_f32_e32 v33, v33
	v_rcp_f32_e32 v34, v34
	v_rcp_f32_e32 v35, v35
	v_rcp_f32_e32 v36, v36
	v_rcp_f32_e32 v37, v37
	v_rcp_f32_e32 v38, v38
	v_rcp_f32_e32 v39, v39
	v_rcp_f32_e32 v40, v40
	v_rcp_f32_e32 v41, v41
	v_rcp_f32_e32 v42, v42
	v_rcp_f32_e32 v43, v43
	v_rcp_f32_e32 v44, v44
	v_rcp_f32_e32 v45, v45
	v_rcp_f32_e32 v46, v46
	v_rcp_f32_e32 v47, v47
	v_rcp_f32_e32 v48, v48
	v_rcp_f32_e32 v49, v49
	v_rcp_f32_e32 v50, v50
	v_rcp_f32_e32 v51, v51
	v_rcp_f32_e32 v52, v52
	v_rcp_f32_e32 v53, v53
	v_rcp_f32_e32 v54, v54
	v_rcp_f32_e32 v55, v55
	v_rcp_f32_e32 v56, v56
	v_rcp_f32_e32 v57, v57
	v_rcp_f32_e32 v58, v58
	v_rcp_f32_e32 v59, v59
	v_rcp_f32_e32 v60, v60
	v_rcp_f32_e32 v61, v61
	v_rcp_f32_e32 v62, v62
	v_rcp_f32_e32 v63, v63
	s_nop 0
	v_cvt_pk_bf16_f32 v32, v32, v33
	v_cvt_pk_bf16_f32 v33, v34, v35
	v_cvt_pk_bf16_f32 v34, v36, v37
	v_cvt_pk_bf16_f32 v35, v38, v39
	v_cvt_pk_bf16_f32 v36, v40, v41
	v_cvt_pk_bf16_f32 v37, v42, v43
	v_cvt_pk_bf16_f32 v38, v44, v45
	v_cvt_pk_bf16_f32 v39, v46, v47
	v_cvt_pk_bf16_f32 v48, v48, v49
	v_cvt_pk_bf16_f32 v49, v50, v51
	v_cvt_pk_bf16_f32 v50, v52, v53
	v_cvt_pk_bf16_f32 v51, v54, v55
	v_cvt_pk_bf16_f32 v52, v56, v57
	v_cvt_pk_bf16_f32 v53, v58, v59
	v_cvt_pk_bf16_f32 v54, v60, v61
	v_cvt_pk_bf16_f32 v55, v62, v63
	v_permlane32_swap_b32_e32 v32, v34
	v_permlane32_swap_b32_e32 v33, v35
	v_permlane32_swap_b32_e32 v36, v38
	v_permlane32_swap_b32_e32 v37, v39
	v_permlane32_swap_b32_e32 v48, v50
	v_permlane32_swap_b32_e32 v49, v51
	v_permlane32_swap_b32_e32 v52, v54
	v_permlane32_swap_b32_e32 v53, v55
	global_store_dwordx4 v181, v[32:35], s[74:75] offset:0
	global_store_dwordx4 v181, v[36:39], s[74:75] offset:32
	global_store_dwordx4 v181, v[48:51], s[74:75] offset:64
	global_store_dwordx4 v181, v[52:55], s[74:75] offset:96
	s_add_u32 s74, s74, 0x44000
	s_addc_u32 s75, s75, 0
	v_pk_fma_f32 v[64:65], v[64:65], v[174:175], v[198:199] op_sel_hi:[1,0,1]
	v_pk_fma_f32 v[66:67], v[66:67], v[174:175], v[200:201] op_sel_hi:[1,0,1]
	v_pk_fma_f32 v[68:69], v[68:69], v[174:175], v[202:203] op_sel_hi:[1,0,1]
	v_pk_fma_f32 v[70:71], v[70:71], v[174:175], v[204:205] op_sel_hi:[1,0,1]
	v_pk_fma_f32 v[72:73], v[72:73], v[174:175], v[206:207] op_sel_hi:[1,0,1]
	v_pk_fma_f32 v[74:75], v[74:75], v[174:175], v[208:209] op_sel_hi:[1,0,1]
	v_pk_fma_f32 v[76:77], v[76:77], v[174:175], v[210:211] op_sel_hi:[1,0,1]
	v_pk_fma_f32 v[78:79], v[78:79], v[174:175], v[212:213] op_sel_hi:[1,0,1]
	v_pk_fma_f32 v[80:81], v[80:81], v[174:175], v[214:215] op_sel_hi:[1,0,1]
	v_pk_fma_f32 v[82:83], v[82:83], v[174:175], v[216:217] op_sel_hi:[1,0,1]
	v_pk_fma_f32 v[84:85], v[84:85], v[174:175], v[218:219] op_sel_hi:[1,0,1]
	v_pk_fma_f32 v[86:87], v[86:87], v[174:175], v[220:221] op_sel_hi:[1,0,1]
	v_pk_fma_f32 v[88:89], v[88:89], v[174:175], v[222:223] op_sel_hi:[1,0,1]
	v_pk_fma_f32 v[90:91], v[90:91], v[174:175], v[224:225] op_sel_hi:[1,0,1]
	v_pk_fma_f32 v[92:93], v[92:93], v[174:175], v[226:227] op_sel_hi:[1,0,1]
	v_pk_fma_f32 v[94:95], v[94:95], v[174:175], v[228:229] op_sel_hi:[1,0,1]
	v_exp_f32_e32 v64, v64
	v_exp_f32_e32 v65, v65
	v_exp_f32_e32 v66, v66
	v_exp_f32_e32 v67, v67
	v_exp_f32_e32 v68, v68
	v_exp_f32_e32 v69, v69
	v_exp_f32_e32 v70, v70
	v_exp_f32_e32 v71, v71
	v_exp_f32_e32 v72, v72
	v_exp_f32_e32 v73, v73
	v_exp_f32_e32 v74, v74
	v_exp_f32_e32 v75, v75
	v_exp_f32_e32 v76, v76
	v_exp_f32_e32 v77, v77
	v_exp_f32_e32 v78, v78
	v_exp_f32_e32 v79, v79
	v_exp_f32_e32 v80, v80
	v_exp_f32_e32 v81, v81
	v_exp_f32_e32 v82, v82
	v_exp_f32_e32 v83, v83
	v_exp_f32_e32 v84, v84
	v_exp_f32_e32 v85, v85
	v_exp_f32_e32 v86, v86
	v_exp_f32_e32 v87, v87
	v_exp_f32_e32 v88, v88
	v_exp_f32_e32 v89, v89
	v_exp_f32_e32 v90, v90
	v_exp_f32_e32 v91, v91
	v_exp_f32_e32 v92, v92
	v_exp_f32_e32 v93, v93
	v_exp_f32_e32 v94, v94
	v_exp_f32_e32 v95, v95
	v_pk_add_f32 v[64:65], v[64:65], 1.0 op_sel_hi:[1,0]
	v_pk_add_f32 v[66:67], v[66:67], 1.0 op_sel_hi:[1,0]
	v_pk_add_f32 v[68:69], v[68:69], 1.0 op_sel_hi:[1,0]
	v_pk_add_f32 v[70:71], v[70:71], 1.0 op_sel_hi:[1,0]
	v_pk_add_f32 v[72:73], v[72:73], 1.0 op_sel_hi:[1,0]
	v_pk_add_f32 v[74:75], v[74:75], 1.0 op_sel_hi:[1,0]
	v_pk_add_f32 v[76:77], v[76:77], 1.0 op_sel_hi:[1,0]
	v_pk_add_f32 v[78:79], v[78:79], 1.0 op_sel_hi:[1,0]
	v_pk_add_f32 v[80:81], v[80:81], 1.0 op_sel_hi:[1,0]
	v_pk_add_f32 v[82:83], v[82:83], 1.0 op_sel_hi:[1,0]
	v_pk_add_f32 v[84:85], v[84:85], 1.0 op_sel_hi:[1,0]
	v_pk_add_f32 v[86:87], v[86:87], 1.0 op_sel_hi:[1,0]
	v_pk_add_f32 v[88:89], v[88:89], 1.0 op_sel_hi:[1,0]
	v_pk_add_f32 v[90:91], v[90:91], 1.0 op_sel_hi:[1,0]
	v_pk_add_f32 v[92:93], v[92:93], 1.0 op_sel_hi:[1,0]
	v_pk_add_f32 v[94:95], v[94:95], 1.0 op_sel_hi:[1,0]
	v_rcp_f32_e32 v64, v64
	v_rcp_f32_e32 v65, v65
	v_rcp_f32_e32 v66, v66
	v_rcp_f32_e32 v67, v67
	v_rcp_f32_e32 v68, v68
	v_rcp_f32_e32 v69, v69
	v_rcp_f32_e32 v70, v70
	v_rcp_f32_e32 v71, v71
	v_rcp_f32_e32 v72, v72
	v_rcp_f32_e32 v73, v73
	v_rcp_f32_e32 v74, v74
	v_rcp_f32_e32 v75, v75
	v_rcp_f32_e32 v76, v76
	v_rcp_f32_e32 v77, v77
	v_rcp_f32_e32 v78, v78
	v_rcp_f32_e32 v79, v79
	v_rcp_f32_e32 v80, v80
	v_rcp_f32_e32 v81, v81
	v_rcp_f32_e32 v82, v82
	v_rcp_f32_e32 v83, v83
	v_rcp_f32_e32 v84, v84
	v_rcp_f32_e32 v85, v85
	v_rcp_f32_e32 v86, v86
	v_rcp_f32_e32 v87, v87
	v_rcp_f32_e32 v88, v88
	v_rcp_f32_e32 v89, v89
	v_rcp_f32_e32 v90, v90
	v_rcp_f32_e32 v91, v91
	v_rcp_f32_e32 v92, v92
	v_rcp_f32_e32 v93, v93
	v_rcp_f32_e32 v94, v94
	v_rcp_f32_e32 v95, v95
	s_nop 0
	v_cvt_pk_bf16_f32 v64, v64, v65
	v_cvt_pk_bf16_f32 v65, v66, v67
	v_cvt_pk_bf16_f32 v66, v68, v69
	v_cvt_pk_bf16_f32 v67, v70, v71
	v_cvt_pk_bf16_f32 v68, v72, v73
	v_cvt_pk_bf16_f32 v69, v74, v75
	v_cvt_pk_bf16_f32 v70, v76, v77
	v_cvt_pk_bf16_f32 v71, v78, v79
	v_cvt_pk_bf16_f32 v80, v80, v81
	v_cvt_pk_bf16_f32 v81, v82, v83
	v_cvt_pk_bf16_f32 v82, v84, v85
	v_cvt_pk_bf16_f32 v83, v86, v87
	v_cvt_pk_bf16_f32 v84, v88, v89
	v_cvt_pk_bf16_f32 v85, v90, v91
	v_cvt_pk_bf16_f32 v86, v92, v93
	v_cvt_pk_bf16_f32 v87, v94, v95
	v_permlane32_swap_b32_e32 v64, v66
	v_permlane32_swap_b32_e32 v65, v67
	v_permlane32_swap_b32_e32 v68, v70
	v_permlane32_swap_b32_e32 v69, v71
	v_permlane32_swap_b32_e32 v80, v82
	v_permlane32_swap_b32_e32 v81, v83
	v_permlane32_swap_b32_e32 v84, v86
	v_permlane32_swap_b32_e32 v85, v87
	global_store_dwordx4 v181, v[64:67], s[74:75] offset:0
	global_store_dwordx4 v181, v[68:71], s[74:75] offset:32
	global_store_dwordx4 v181, v[80:83], s[74:75] offset:64
	global_store_dwordx4 v181, v[84:87], s[74:75] offset:96
	s_add_u32 s74, s74, 0x44000
	s_addc_u32 s75, s75, 0
	v_pk_fma_f32 v[96:97], v[96:97], v[174:175], v[198:199] op_sel:[0,1,0] op_sel_hi:[1,1,1]
	v_pk_fma_f32 v[98:99], v[98:99], v[174:175], v[200:201] op_sel:[0,1,0] op_sel_hi:[1,1,1]
	v_pk_fma_f32 v[100:101], v[100:101], v[174:175], v[202:203] op_sel:[0,1,0] op_sel_hi:[1,1,1]
	v_pk_fma_f32 v[102:103], v[102:103], v[174:175], v[204:205] op_sel:[0,1,0] op_sel_hi:[1,1,1]
	v_pk_fma_f32 v[104:105], v[104:105], v[174:175], v[206:207] op_sel:[0,1,0] op_sel_hi:[1,1,1]
	v_pk_fma_f32 v[106:107], v[106:107], v[174:175], v[208:209] op_sel:[0,1,0] op_sel_hi:[1,1,1]
	v_pk_fma_f32 v[108:109], v[108:109], v[174:175], v[210:211] op_sel:[0,1,0] op_sel_hi:[1,1,1]
	v_pk_fma_f32 v[110:111], v[110:111], v[174:175], v[212:213] op_sel:[0,1,0] op_sel_hi:[1,1,1]
	v_pk_fma_f32 v[112:113], v[112:113], v[174:175], v[214:215] op_sel:[0,1,0] op_sel_hi:[1,1,1]
	v_pk_fma_f32 v[114:115], v[114:115], v[174:175], v[216:217] op_sel:[0,1,0] op_sel_hi:[1,1,1]
	v_pk_fma_f32 v[116:117], v[116:117], v[174:175], v[218:219] op_sel:[0,1,0] op_sel_hi:[1,1,1]
	v_pk_fma_f32 v[118:119], v[118:119], v[174:175], v[220:221] op_sel:[0,1,0] op_sel_hi:[1,1,1]
	v_pk_fma_f32 v[120:121], v[120:121], v[174:175], v[222:223] op_sel:[0,1,0] op_sel_hi:[1,1,1]
	v_pk_fma_f32 v[122:123], v[122:123], v[174:175], v[224:225] op_sel:[0,1,0] op_sel_hi:[1,1,1]
	v_pk_fma_f32 v[124:125], v[124:125], v[174:175], v[226:227] op_sel:[0,1,0] op_sel_hi:[1,1,1]
	v_pk_fma_f32 v[126:127], v[126:127], v[174:175], v[228:229] op_sel:[0,1,0] op_sel_hi:[1,1,1]
	v_exp_f32_e32 v96, v96
	v_exp_f32_e32 v97, v97
	v_exp_f32_e32 v98, v98
	v_exp_f32_e32 v99, v99
	v_exp_f32_e32 v100, v100
	v_exp_f32_e32 v101, v101
	v_exp_f32_e32 v102, v102
	v_exp_f32_e32 v103, v103
	v_exp_f32_e32 v104, v104
	v_exp_f32_e32 v105, v105
	v_exp_f32_e32 v106, v106
	v_exp_f32_e32 v107, v107
	v_exp_f32_e32 v108, v108
	v_exp_f32_e32 v109, v109
	v_exp_f32_e32 v110, v110
	v_exp_f32_e32 v111, v111
	v_exp_f32_e32 v112, v112
	v_exp_f32_e32 v113, v113
	v_exp_f32_e32 v114, v114
	v_exp_f32_e32 v115, v115
	v_exp_f32_e32 v116, v116
	v_exp_f32_e32 v117, v117
	v_exp_f32_e32 v118, v118
	v_exp_f32_e32 v119, v119
	v_exp_f32_e32 v120, v120
	v_exp_f32_e32 v121, v121
	v_exp_f32_e32 v122, v122
	v_exp_f32_e32 v123, v123
	v_exp_f32_e32 v124, v124
	v_exp_f32_e32 v125, v125
	v_exp_f32_e32 v126, v126
	v_exp_f32_e32 v127, v127
	v_pk_add_f32 v[96:97], v[96:97], 1.0 op_sel_hi:[1,0]
	v_pk_add_f32 v[98:99], v[98:99], 1.0 op_sel_hi:[1,0]
	v_pk_add_f32 v[100:101], v[100:101], 1.0 op_sel_hi:[1,0]
	v_pk_add_f32 v[102:103], v[102:103], 1.0 op_sel_hi:[1,0]
	v_pk_add_f32 v[104:105], v[104:105], 1.0 op_sel_hi:[1,0]
	v_pk_add_f32 v[106:107], v[106:107], 1.0 op_sel_hi:[1,0]
	v_pk_add_f32 v[108:109], v[108:109], 1.0 op_sel_hi:[1,0]
	v_pk_add_f32 v[110:111], v[110:111], 1.0 op_sel_hi:[1,0]
	v_pk_add_f32 v[112:113], v[112:113], 1.0 op_sel_hi:[1,0]
	v_pk_add_f32 v[114:115], v[114:115], 1.0 op_sel_hi:[1,0]
	v_pk_add_f32 v[116:117], v[116:117], 1.0 op_sel_hi:[1,0]
	v_pk_add_f32 v[118:119], v[118:119], 1.0 op_sel_hi:[1,0]
	v_pk_add_f32 v[120:121], v[120:121], 1.0 op_sel_hi:[1,0]
	v_pk_add_f32 v[122:123], v[122:123], 1.0 op_sel_hi:[1,0]
	v_pk_add_f32 v[124:125], v[124:125], 1.0 op_sel_hi:[1,0]
	v_pk_add_f32 v[126:127], v[126:127], 1.0 op_sel_hi:[1,0]
	v_rcp_f32_e32 v96, v96
	v_rcp_f32_e32 v97, v97
	v_rcp_f32_e32 v98, v98
	v_rcp_f32_e32 v99, v99
	v_rcp_f32_e32 v100, v100
	v_rcp_f32_e32 v101, v101
	v_rcp_f32_e32 v102, v102
	v_rcp_f32_e32 v103, v103
	v_rcp_f32_e32 v104, v104
	v_rcp_f32_e32 v105, v105
	v_rcp_f32_e32 v106, v106
	v_rcp_f32_e32 v107, v107
	v_rcp_f32_e32 v108, v108
	v_rcp_f32_e32 v109, v109
	v_rcp_f32_e32 v110, v110
	v_rcp_f32_e32 v111, v111
	v_rcp_f32_e32 v112, v112
	v_rcp_f32_e32 v113, v113
	v_rcp_f32_e32 v114, v114
	v_rcp_f32_e32 v115, v115
	v_rcp_f32_e32 v116, v116
	v_rcp_f32_e32 v117, v117
	v_rcp_f32_e32 v118, v118
	v_rcp_f32_e32 v119, v119
	v_rcp_f32_e32 v120, v120
	v_rcp_f32_e32 v121, v121
	v_rcp_f32_e32 v122, v122
	v_rcp_f32_e32 v123, v123
	v_rcp_f32_e32 v124, v124
	v_rcp_f32_e32 v125, v125
	v_rcp_f32_e32 v126, v126
	v_rcp_f32_e32 v127, v127
	s_nop 0
	v_cvt_pk_bf16_f32 v96, v96, v97
	v_cvt_pk_bf16_f32 v97, v98, v99
	v_cvt_pk_bf16_f32 v98, v100, v101
	v_cvt_pk_bf16_f32 v99, v102, v103
	v_cvt_pk_bf16_f32 v100, v104, v105
	v_cvt_pk_bf16_f32 v101, v106, v107
	v_cvt_pk_bf16_f32 v102, v108, v109
	v_cvt_pk_bf16_f32 v103, v110, v111
	v_cvt_pk_bf16_f32 v112, v112, v113
	v_cvt_pk_bf16_f32 v113, v114, v115
	v_cvt_pk_bf16_f32 v114, v116, v117
	v_cvt_pk_bf16_f32 v115, v118, v119
	v_cvt_pk_bf16_f32 v116, v120, v121
	v_cvt_pk_bf16_f32 v117, v122, v123
	v_cvt_pk_bf16_f32 v118, v124, v125
	v_cvt_pk_bf16_f32 v119, v126, v127
	v_permlane32_swap_b32_e32 v96, v98
	v_permlane32_swap_b32_e32 v97, v99
	v_permlane32_swap_b32_e32 v100, v102
	v_permlane32_swap_b32_e32 v101, v103
	v_permlane32_swap_b32_e32 v112, v114
	v_permlane32_swap_b32_e32 v113, v115
	v_permlane32_swap_b32_e32 v116, v118
	v_permlane32_swap_b32_e32 v117, v119
	global_store_dwordx4 v181, v[96:99], s[74:75] offset:0
	global_store_dwordx4 v181, v[100:103], s[74:75] offset:32
	global_store_dwordx4 v181, v[112:115], s[74:75] offset:64
	global_store_dwordx4 v181, v[116:119], s[74:75] offset:96
	s_branch .Lpe_ret_L1
.Lpe_vt_L1:
	s_lshl_b32 s35, s34, 2
	s_add_u32 s35, s35, s28
	s_add_u32 s36, s28, 6
	s_cmp_eq_u32 s25, 8
	s_cselect_b32 s35, s36, s35
	s_lshr_b32 s36, s29, 11
	s_mul_i32 s36, s36, 10
	s_add_u32 s36, s36, s35
	s_lshl_b32 s36, s36, 18
	s_and_b32 s37, s29, 0x7ff
	s_lshl_b32 s37, s37, 1
	s_add_u32 s36, s36, s37
	s_add_u32 s38, s72, 0x14920000
	s_addc_u32 s39, s73, 0
	s_add_u32 s38, s38, s36
	s_addc_u32 s39, s39, 0
	s_mul_i32 s36, s26, 10240
	s_add_u32 s36, s36, 0x10000
	v_lshlrev_b32_e32 v180, 1, v197
	v_mul_u32_u24_e32 v181, 36, v146
	v_add3_u32 v180, v180, v181, s36
	v_lshrrev_b32_e32 v181, 3, v179
	v_and_b32_e32 v146, 7, v179
	v_lshlrev_b32_e32 v146, 4, v146
	v_mul_u32_u24_e32 v198, 144, v181
	v_add3_u32 v198, v198, v146, s36
	v_lshl_add_u32 v199, v181, 12, v146
	s_waitcnt vmcnt(0)
	v_mov_b32_e32 v197, 0x358637bd
	v_pk_add_f32 v[128:129], v[128:129], v[130:131]
	v_pk_add_f32 v[132:133], v[132:133], v[134:135]
	v_pk_add_f32 v[136:137], v[136:137], v[138:139]
	v_pk_add_f32 v[140:141], v[140:141], v[142:143]
	v_pk_add_f32 v[164:165], v[164:165], v[166:167]
	v_pk_add_f32 v[168:169], v[168:169], v[170:171]
	v_pk_add_f32 v[246:247], v[246:247], v[248:249]
	v_pk_add_f32 v[250:251], v[250:251], v[252:253]
	v_pk_add_f32 v[128:129], v[128:129], v[132:133]
	v_pk_add_f32 v[136:137], v[136:137], v[140:141]
	v_pk_add_f32 v[164:165], v[164:165], v[168:169]
	v_pk_add_f32 v[246:247], v[246:247], v[250:251]
	v_add_f32_e32 v128, v128, v129
	v_add_f32_e32 v136, v136, v137
	v_add_f32_e32 v164, v164, v165
	v_add_f32_e32 v246, v246, v247
	v_fmamk_f32 v128, v128, 0x3a800000, v197
	v_fmamk_f32 v136, v136, 0x3a800000, v197
	v_fmamk_f32 v164, v164, 0x3a800000, v197
	v_fmamk_f32 v246, v246, 0x3a800000, v197
	v_rsq_f32_e32 v172, v128
	v_rsq_f32_e32 v173, v136
	v_rsq_f32_e32 v174, v164
	v_rsq_f32_e32 v175, v246
	s_nop 0
	s_add_u32 s76, s99, s90
	s_cmp_lt_u32 s76, 0x440
	s_cselect_b32 s80, 1, 0
	s_cselect_b32 s83, 0x200000, 0
	s_lshl_b32 s76, s24, 19
	s_lshl_b32 s77, s26, 16
	s_add_u32 s76, s76, s77
	s_and_b32 s77, s24, 7
	s_lshl_b32 s77, s77, 8
	s_and_b32 s82, s25, 3
	s_lshl_b32 s82, s82, 9
	s_add_u32 s77, s77, s82
	s_and_b32 s77, s77, 0x7ff
	s_add_u32 s76, s76, s77
	s_add_u32 s78, s72, 0xa120000
	s_addc_u32 s79, s73, 0
	s_add_u32 s78, s78, s76
	s_addc_u32 s79, s79, 0
	s_lshl_b32 s76, s25, 19
	s_add_u32 s76, s76, s83
	s_add_u32 s76, s76, s77
	s_lshl_b32 s77, s26, 16
	s_add_u32 s76, s76, s77
	s_add_u32 s82, s72, 0x880000
	s_addc_u32 s83, s73, 0
	s_add_u32 s82, s82, s76
	s_addc_u32 s83, s83, 0
	s_lshl_b32 s76, s26, 12
	s_mov_b32 m0, s76
	s_nop 0
	global_load_lds_dwordx4 v177, s[78:79]
	s_add_u32 s78, s78, 0x4000
	s_addc_u32 s79, s79, 0
	s_add_u32 s76, s76, 0x400
	s_mov_b32 m0, s76
	s_nop 0
	global_load_lds_dwordx4 v185, s[78:79]
	s_add_u32 s78, s78, 0x4000
	s_addc_u32 s79, s79, 0
	s_add_u32 s76, s76, 0x400
	s_mov_b32 m0, s76
	s_nop 0
	global_load_lds_dwordx4 v177, s[78:79]
	s_add_u32 s78, s78, 0x4000
	s_addc_u32 s79, s79, 0
	s_add_u32 s76, s76, 0x400
	s_mov_b32 m0, s76
	s_nop 0
	global_load_lds_dwordx4 v185, s[78:79]
	s_add_u32 s78, s78, 0x4000
	s_addc_u32 s79, s79, 0
	s_add_u32 s76, s76, 0x400
	s_add_u32 s76, s76, 0x7000
	s_mov_b32 m0, s76
	s_nop 0
	global_load_lds_dwordx4 v177, s[82:83]
	s_add_u32 s82, s82, 0x4000
	s_addc_u32 s83, s83, 0
	s_add_u32 s76, s76, 0x400
	s_mov_b32 m0, s76
	s_nop 0
	global_load_lds_dwordx4 v185, s[82:83]
	s_add_u32 s82, s82, 0x4000
	s_addc_u32 s83, s83, 0
	s_add_u32 s76, s76, 0x400
	s_mov_b32 m0, s76
	s_nop 0
	global_load_lds_dwordx4 v177, s[82:83]
	s_add_u32 s82, s82, 0x4000
	s_addc_u32 s83, s83, 0
	s_add_u32 s76, s76, 0x400
	s_mov_b32 m0, s76
	s_nop 0
	global_load_lds_dwordx4 v185, s[82:83]
	s_add_u32 s82, s82, 0x4000
	s_addc_u32 s83, s83, 0
	s_add_u32 s76, s76, 0x400
	v_pk_mul_f32 v[0:1], v[0:1], v[172:173] op_sel_hi:[1,0]
	v_pk_mul_f32 v[2:3], v[2:3], v[172:173] op_sel_hi:[1,0]
	v_pk_mul_f32 v[4:5], v[4:5], v[172:173] op_sel_hi:[1,0]
	v_pk_mul_f32 v[6:7], v[6:7], v[172:173] op_sel_hi:[1,0]
	v_pk_mul_f32 v[8:9], v[8:9], v[172:173] op_sel_hi:[1,0]
	v_pk_mul_f32 v[10:11], v[10:11], v[172:173] op_sel_hi:[1,0]
	v_pk_mul_f32 v[12:13], v[12:13], v[172:173] op_sel_hi:[1,0]
	v_pk_mul_f32 v[14:15], v[14:15], v[172:173] op_sel_hi:[1,0]
	v_pk_mul_f32 v[16:17], v[16:17], v[172:173] op_sel_hi:[1,0]
	v_pk_mul_f32 v[18:19], v[18:19], v[172:173] op_sel_hi:[1,0]
	v_pk_mul_f32 v[20:21], v[20:21], v[172:173] op_sel_hi:[1,0]
	v_pk_mul_f32 v[22:23], v[22:23], v[172:173] op_sel_hi:[1,0]
	v_pk_mul_f32 v[24:25], v[24:25], v[172:173] op_sel_hi:[1,0]
	v_pk_mul_f32 v[26:27], v[26:27], v[172:173] op_sel_hi:[1,0]
	v_pk_mul_f32 v[28:29], v[28:29], v[172:173] op_sel_hi:[1,0]
	v_pk_mul_f32 v[30:31], v[30:31], v[172:173] op_sel_hi:[1,0]
	v_pk_mul_f32 v[32:33], v[32:33], v[172:173] op_sel:[0,1] op_sel_hi:[1,1]
	v_pk_mul_f32 v[34:35], v[34:35], v[172:173] op_sel:[0,1] op_sel_hi:[1,1]
	v_pk_mul_f32 v[36:37], v[36:37], v[172:173] op_sel:[0,1] op_sel_hi:[1,1]
	v_pk_mul_f32 v[38:39], v[38:39], v[172:173] op_sel:[0,1] op_sel_hi:[1,1]
	v_pk_mul_f32 v[40:41], v[40:41], v[172:173] op_sel:[0,1] op_sel_hi:[1,1]
	v_pk_mul_f32 v[42:43], v[42:43], v[172:173] op_sel:[0,1] op_sel_hi:[1,1]
	v_pk_mul_f32 v[44:45], v[44:45], v[172:173] op_sel:[0,1] op_sel_hi:[1,1]
	v_pk_mul_f32 v[46:47], v[46:47], v[172:173] op_sel:[0,1] op_sel_hi:[1,1]
	v_pk_mul_f32 v[48:49], v[48:49], v[172:173] op_sel:[0,1] op_sel_hi:[1,1]
	v_pk_mul_f32 v[50:51], v[50:51], v[172:173] op_sel:[0,1] op_sel_hi:[1,1]
	v_pk_mul_f32 v[52:53], v[52:53], v[172:173] op_sel:[0,1] op_sel_hi:[1,1]
	v_pk_mul_f32 v[54:55], v[54:55], v[172:173] op_sel:[0,1] op_sel_hi:[1,1]
	v_pk_mul_f32 v[56:57], v[56:57], v[172:173] op_sel:[0,1] op_sel_hi:[1,1]
	v_pk_mul_f32 v[58:59], v[58:59], v[172:173] op_sel:[0,1] op_sel_hi:[1,1]
	v_pk_mul_f32 v[60:61], v[60:61], v[172:173] op_sel:[0,1] op_sel_hi:[1,1]
	v_pk_mul_f32 v[62:63], v[62:63], v[172:173] op_sel:[0,1] op_sel_hi:[1,1]
	v_pk_mul_f32 v[64:65], v[64:65], v[174:175] op_sel_hi:[1,0]
	v_pk_mul_f32 v[66:67], v[66:67], v[174:175] op_sel_hi:[1,0]
	v_pk_mul_f32 v[68:69], v[68:69], v[174:175] op_sel_hi:[1,0]
	v_pk_mul_f32 v[70:71], v[70:71], v[174:175] op_sel_hi:[1,0]
	v_pk_mul_f32 v[72:73], v[72:73], v[174:175] op_sel_hi:[1,0]
	v_pk_mul_f32 v[74:75], v[74:75], v[174:175] op_sel_hi:[1,0]
	v_pk_mul_f32 v[76:77], v[76:77], v[174:175] op_sel_hi:[1,0]
	v_pk_mul_f32 v[78:79], v[78:79], v[174:175] op_sel_hi:[1,0]
	v_pk_mul_f32 v[80:81], v[80:81], v[174:175] op_sel_hi:[1,0]
	v_pk_mul_f32 v[82:83], v[82:83], v[174:175] op_sel_hi:[1,0]
	v_pk_mul_f32 v[84:85], v[84:85], v[174:175] op_sel_hi:[1,0]
	v_pk_mul_f32 v[86:87], v[86:87], v[174:175] op_sel_hi:[1,0]
	v_pk_mul_f32 v[88:89], v[88:89], v[174:175] op_sel_hi:[1,0]
	v_pk_mul_f32 v[90:91], v[90:91], v[174:175] op_sel_hi:[1,0]
	v_pk_mul_f32 v[92:93], v[92:93], v[174:175] op_sel_hi:[1,0]
	v_pk_mul_f32 v[94:95], v[94:95], v[174:175] op_sel_hi:[1,0]
	v_pk_mul_f32 v[96:97], v[96:97], v[174:175] op_sel:[0,1] op_sel_hi:[1,1]
	v_pk_mul_f32 v[98:99], v[98:99], v[174:175] op_sel:[0,1] op_sel_hi:[1,1]
	v_pk_mul_f32 v[100:101], v[100:101], v[174:175] op_sel:[0,1] op_sel_hi:[1,1]
	v_pk_mul_f32 v[102:103], v[102:103], v[174:175] op_sel:[0,1] op_sel_hi:[1,1]
	v_pk_mul_f32 v[104:105], v[104:105], v[174:175] op_sel:[0,1] op_sel_hi:[1,1]
	v_pk_mul_f32 v[106:107], v[106:107], v[174:175] op_sel:[0,1] op_sel_hi:[1,1]
	v_pk_mul_f32 v[108:109], v[108:109], v[174:175] op_sel:[0,1] op_sel_hi:[1,1]
	v_pk_mul_f32 v[110:111], v[110:111], v[174:175] op_sel:[0,1] op_sel_hi:[1,1]
	v_pk_mul_f32 v[112:113], v[112:113], v[174:175] op_sel:[0,1] op_sel_hi:[1,1]
	v_pk_mul_f32 v[114:115], v[114:115], v[174:175] op_sel:[0,1] op_sel_hi:[1,1]
	v_pk_mul_f32 v[116:117], v[116:117], v[174:175] op_sel:[0,1] op_sel_hi:[1,1]
	v_pk_mul_f32 v[118:119], v[118:119], v[174:175] op_sel:[0,1] op_sel_hi:[1,1]
	v_pk_mul_f32 v[120:121], v[120:121], v[174:175] op_sel:[0,1] op_sel_hi:[1,1]
	v_pk_mul_f32 v[122:123], v[122:123], v[174:175] op_sel:[0,1] op_sel_hi:[1,1]
	v_pk_mul_f32 v[124:125], v[124:125], v[174:175] op_sel:[0,1] op_sel_hi:[1,1]
	v_pk_mul_f32 v[126:127], v[126:127], v[174:175] op_sel:[0,1] op_sel_hi:[1,1]
	v_cvt_pk_bf16_f32 v0, v0, v1
	v_cvt_pk_bf16_f32 v1, v2, v3
	v_cvt_pk_bf16_f32 v2, v4, v5
	v_cvt_pk_bf16_f32 v3, v6, v7
	v_cvt_pk_bf16_f32 v4, v8, v9
	v_cvt_pk_bf16_f32 v5, v10, v11
	v_cvt_pk_bf16_f32 v6, v12, v13
	v_cvt_pk_bf16_f32 v7, v14, v15
	ds_write_b16 v180, v0 offset:0
	ds_write_b16_d16_hi v180, v0 offset:144
	ds_write_b16 v180, v1 offset:288
	ds_write_b16_d16_hi v180, v1 offset:432
	ds_write_b16 v180, v2 offset:1152
	ds_write_b16_d16_hi v180, v2 offset:1296
	ds_write_b16 v180, v3 offset:1440
	ds_write_b16_d16_hi v180, v3 offset:1584
	ds_write_b16 v180, v4 offset:2304
	ds_write_b16_d16_hi v180, v4 offset:2448
	ds_write_b16 v180, v5 offset:2592
	ds_write_b16_d16_hi v180, v5 offset:2736
	ds_write_b16 v180, v6 offset:3456
	ds_write_b16_d16_hi v180, v6 offset:3600
	ds_write_b16 v180, v7 offset:3744
	ds_write_b16_d16_hi v180, v7 offset:3888
	v_cvt_pk_bf16_f32 v16, v16, v17
	v_cvt_pk_bf16_f32 v17, v18, v19
	v_cvt_pk_bf16_f32 v18, v20, v21
	v_cvt_pk_bf16_f32 v19, v22, v23
	v_cvt_pk_bf16_f32 v20, v24, v25
	v_cvt_pk_bf16_f32 v21, v26, v27
	v_cvt_pk_bf16_f32 v22, v28, v29
	v_cvt_pk_bf16_f32 v23, v30, v31
	ds_write_b16 v180, v16 offset:4608
	ds_write_b16_d16_hi v180, v16 offset:4752
	ds_write_b16 v180, v17 offset:4896
	ds_write_b16_d16_hi v180, v17 offset:5040
	ds_write_b16 v180, v18 offset:5760
	ds_write_b16_d16_hi v180, v18 offset:5904
	ds_write_b16 v180, v19 offset:6048
	ds_write_b16_d16_hi v180, v19 offset:6192
	ds_write_b16 v180, v20 offset:6912
	ds_write_b16_d16_hi v180, v20 offset:7056
	ds_write_b16 v180, v21 offset:7200
	ds_write_b16_d16_hi v180, v21 offset:7344
	ds_write_b16 v180, v22 offset:8064
	ds_write_b16_d16_hi v180, v22 offset:8208
	ds_write_b16 v180, v23 offset:8352
	ds_write_b16_d16_hi v180, v23 offset:8496
	v_cvt_pk_bf16_f32 v32, v32, v33
	v_cvt_pk_bf16_f32 v33, v34, v35
	v_cvt_pk_bf16_f32 v34, v36, v37
	v_cvt_pk_bf16_f32 v35, v38, v39
	v_cvt_pk_bf16_f32 v36, v40, v41
	v_cvt_pk_bf16_f32 v37, v42, v43
	v_cvt_pk_bf16_f32 v38, v44, v45
	v_cvt_pk_bf16_f32 v39, v46, v47
	ds_write_b16 v180, v32 offset:64
	ds_write_b16_d16_hi v180, v32 offset:208
	ds_write_b16 v180, v33 offset:352
	ds_write_b16_d16_hi v180, v33 offset:496
	ds_write_b16 v180, v34 offset:1216
	ds_write_b16_d16_hi v180, v34 offset:1360
	ds_write_b16 v180, v35 offset:1504
	ds_write_b16_d16_hi v180, v35 offset:1648
	ds_write_b16 v180, v36 offset:2368
	ds_write_b16_d16_hi v180, v36 offset:2512
	ds_write_b16 v180, v37 offset:2656
	ds_write_b16_d16_hi v180, v37 offset:2800
	ds_write_b16 v180, v38 offset:3520
	ds_write_b16_d16_hi v180, v38 offset:3664
	ds_write_b16 v180, v39 offset:3808
	ds_write_b16_d16_hi v180, v39 offset:3952
	v_cvt_pk_bf16_f32 v48, v48, v49
	v_cvt_pk_bf16_f32 v49, v50, v51
	v_cvt_pk_bf16_f32 v50, v52, v53
	v_cvt_pk_bf16_f32 v51, v54, v55
	v_cvt_pk_bf16_f32 v52, v56, v57
	v_cvt_pk_bf16_f32 v53, v58, v59
	v_cvt_pk_bf16_f32 v54, v60, v61
	v_cvt_pk_bf16_f32 v55, v62, v63
	ds_write_b16 v180, v48 offset:4672
	ds_write_b16_d16_hi v180, v48 offset:4816
	ds_write_b16 v180, v49 offset:4960
	ds_write_b16_d16_hi v180, v49 offset:5104
	ds_write_b16 v180, v50 offset:5824
	ds_write_b16_d16_hi v180, v50 offset:5968
	ds_write_b16 v180, v51 offset:6112
	ds_write_b16_d16_hi v180, v51 offset:6256
	ds_write_b16 v180, v52 offset:6976
	ds_write_b16_d16_hi v180, v52 offset:7120
	ds_write_b16 v180, v53 offset:7264
	ds_write_b16_d16_hi v180, v53 offset:7408
	ds_write_b16 v180, v54 offset:8128
	ds_write_b16_d16_hi v180, v54 offset:8272
	ds_write_b16 v180, v55 offset:8416
	ds_write_b16_d16_hi v180, v55 offset:8560
	s_waitcnt lgkmcnt(0)
	ds_read_b128 v[0:3], v198 offset:0
	ds_read_b128 v[4:7], v198 offset:1152
	ds_read_b128 v[8:11], v198 offset:2304
	ds_read_b128 v[12:15], v198 offset:3456
	ds_read_b128 v[16:19], v198 offset:4608
	ds_read_b128 v[20:23], v198 offset:5760
	ds_read_b128 v[24:27], v198 offset:6912
	ds_read_b128 v[28:31], v198 offset:8064
	s_waitcnt lgkmcnt(7)
	global_store_dwordx4 v199, v[0:3], s[38:39]
	s_add_u32 s38, s38, 0x8000
	s_addc_u32 s39, s39, 0
	s_waitcnt lgkmcnt(6)
	global_store_dwordx4 v199, v[4:7], s[38:39]
	s_add_u32 s38, s38, 0x8000
	s_addc_u32 s39, s39, 0
	s_waitcnt lgkmcnt(5)
	global_store_dwordx4 v199, v[8:11], s[38:39]
	s_add_u32 s38, s38, 0x8000
	s_addc_u32 s39, s39, 0
	s_waitcnt lgkmcnt(4)
	global_store_dwordx4 v199, v[12:15], s[38:39]
	s_add_u32 s38, s38, 0x8000
	s_addc_u32 s39, s39, 0
	s_waitcnt lgkmcnt(3)
	global_store_dwordx4 v199, v[16:19], s[38:39]
	s_add_u32 s38, s38, 0x8000
	s_addc_u32 s39, s39, 0
	s_waitcnt lgkmcnt(2)
	global_store_dwordx4 v199, v[20:23], s[38:39]
	s_add_u32 s38, s38, 0x8000
	s_addc_u32 s39, s39, 0
	s_waitcnt lgkmcnt(1)
	global_store_dwordx4 v199, v[24:27], s[38:39]
	s_add_u32 s38, s38, 0x8000
	s_addc_u32 s39, s39, 0
	s_waitcnt lgkmcnt(0)
	global_store_dwordx4 v199, v[28:31], s[38:39]
	s_sub_u32 s38, s38, 229248
	s_subb_u32 s39, s39, 0
	v_cvt_pk_bf16_f32 v64, v64, v65
	v_cvt_pk_bf16_f32 v65, v66, v67
	v_cvt_pk_bf16_f32 v66, v68, v69
	v_cvt_pk_bf16_f32 v67, v70, v71
	v_cvt_pk_bf16_f32 v68, v72, v73
	v_cvt_pk_bf16_f32 v69, v74, v75
	v_cvt_pk_bf16_f32 v70, v76, v77
	v_cvt_pk_bf16_f32 v71, v78, v79
	ds_write_b16 v180, v64 offset:0
	ds_write_b16_d16_hi v180, v64 offset:144
	ds_write_b16 v180, v65 offset:288
	ds_write_b16_d16_hi v180, v65 offset:432
	ds_write_b16 v180, v66 offset:1152
	ds_write_b16_d16_hi v180, v66 offset:1296
	ds_write_b16 v180, v67 offset:1440
	ds_write_b16_d16_hi v180, v67 offset:1584
	ds_write_b16 v180, v68 offset:2304
	ds_write_b16_d16_hi v180, v68 offset:2448
	ds_write_b16 v180, v69 offset:2592
	ds_write_b16_d16_hi v180, v69 offset:2736
	ds_write_b16 v180, v70 offset:3456
	ds_write_b16_d16_hi v180, v70 offset:3600
	ds_write_b16 v180, v71 offset:3744
	ds_write_b16_d16_hi v180, v71 offset:3888
	v_cvt_pk_bf16_f32 v80, v80, v81
	v_cvt_pk_bf16_f32 v81, v82, v83
	v_cvt_pk_bf16_f32 v82, v84, v85
	v_cvt_pk_bf16_f32 v83, v86, v87
	v_cvt_pk_bf16_f32 v84, v88, v89
	v_cvt_pk_bf16_f32 v85, v90, v91
	v_cvt_pk_bf16_f32 v86, v92, v93
	v_cvt_pk_bf16_f32 v87, v94, v95
	ds_write_b16 v180, v80 offset:4608
	ds_write_b16_d16_hi v180, v80 offset:4752
	ds_write_b16 v180, v81 offset:4896
	ds_write_b16_d16_hi v180, v81 offset:5040
	ds_write_b16 v180, v82 offset:5760
	ds_write_b16_d16_hi v180, v82 offset:5904
	ds_write_b16 v180, v83 offset:6048
	ds_write_b16_d16_hi v180, v83 offset:6192
	ds_write_b16 v180, v84 offset:6912
	ds_write_b16_d16_hi v180, v84 offset:7056
	ds_write_b16 v180, v85 offset:7200
	ds_write_b16_d16_hi v180, v85 offset:7344
	ds_write_b16 v180, v86 offset:8064
	ds_write_b16_d16_hi v180, v86 offset:8208
	ds_write_b16 v180, v87 offset:8352
	ds_write_b16_d16_hi v180, v87 offset:8496
	v_cvt_pk_bf16_f32 v96, v96, v97
	v_cvt_pk_bf16_f32 v97, v98, v99
	v_cvt_pk_bf16_f32 v98, v100, v101
	v_cvt_pk_bf16_f32 v99, v102, v103
	v_cvt_pk_bf16_f32 v100, v104, v105
	v_cvt_pk_bf16_f32 v101, v106, v107
	v_cvt_pk_bf16_f32 v102, v108, v109
	v_cvt_pk_bf16_f32 v103, v110, v111
	ds_write_b16 v180, v96 offset:64
	ds_write_b16_d16_hi v180, v96 offset:208
	ds_write_b16 v180, v97 offset:352
	ds_write_b16_d16_hi v180, v97 offset:496
	ds_write_b16 v180, v98 offset:1216
	ds_write_b16_d16_hi v180, v98 offset:1360
	ds_write_b16 v180, v99 offset:1504
	ds_write_b16_d16_hi v180, v99 offset:1648
	ds_write_b16 v180, v100 offset:2368
	ds_write_b16_d16_hi v180, v100 offset:2512
	ds_write_b16 v180, v101 offset:2656
	ds_write_b16_d16_hi v180, v101 offset:2800
	ds_write_b16 v180, v102 offset:3520
	ds_write_b16_d16_hi v180, v102 offset:3664
	ds_write_b16 v180, v103 offset:3808
	ds_write_b16_d16_hi v180, v103 offset:3952
	v_cvt_pk_bf16_f32 v112, v112, v113
	v_cvt_pk_bf16_f32 v113, v114, v115
	v_cvt_pk_bf16_f32 v114, v116, v117
	v_cvt_pk_bf16_f32 v115, v118, v119
	v_cvt_pk_bf16_f32 v116, v120, v121
	v_cvt_pk_bf16_f32 v117, v122, v123
	v_cvt_pk_bf16_f32 v118, v124, v125
	v_cvt_pk_bf16_f32 v119, v126, v127
	ds_write_b16 v180, v112 offset:4672
	ds_write_b16_d16_hi v180, v112 offset:4816
	ds_write_b16 v180, v113 offset:4960
	ds_write_b16_d16_hi v180, v113 offset:5104
	ds_write_b16 v180, v114 offset:5824
	ds_write_b16_d16_hi v180, v114 offset:5968
	ds_write_b16 v180, v115 offset:6112
	ds_write_b16_d16_hi v180, v115 offset:6256
	ds_write_b16 v180, v116 offset:6976
	ds_write_b16_d16_hi v180, v116 offset:7120
	ds_write_b16 v180, v117 offset:7264
	ds_write_b16_d16_hi v180, v117 offset:7408
	ds_write_b16 v180, v118 offset:8128
	ds_write_b16_d16_hi v180, v118 offset:8272
	ds_write_b16 v180, v119 offset:8416
	ds_write_b16_d16_hi v180, v119 offset:8560
	s_waitcnt lgkmcnt(0)
	ds_read_b128 v[64:67], v198 offset:0
	ds_read_b128 v[68:71], v198 offset:1152
	ds_read_b128 v[72:75], v198 offset:2304
	ds_read_b128 v[76:79], v198 offset:3456
	ds_read_b128 v[80:83], v198 offset:4608
	ds_read_b128 v[84:87], v198 offset:5760
	ds_read_b128 v[88:91], v198 offset:6912
	ds_read_b128 v[92:95], v198 offset:8064
	s_waitcnt lgkmcnt(7)
	global_store_dwordx4 v199, v[64:67], s[38:39]
	s_add_u32 s38, s38, 0x8000
	s_addc_u32 s39, s39, 0
	s_waitcnt lgkmcnt(6)
	global_store_dwordx4 v199, v[68:71], s[38:39]
	s_add_u32 s38, s38, 0x8000
	s_addc_u32 s39, s39, 0
	s_waitcnt lgkmcnt(5)
	global_store_dwordx4 v199, v[72:75], s[38:39]
	s_add_u32 s38, s38, 0x8000
	s_addc_u32 s39, s39, 0
	s_waitcnt lgkmcnt(4)
	global_store_dwordx4 v199, v[76:79], s[38:39]
	s_add_u32 s38, s38, 0x8000
	s_addc_u32 s39, s39, 0
	s_waitcnt lgkmcnt(3)
	global_store_dwordx4 v199, v[80:83], s[38:39]
	s_add_u32 s38, s38, 0x8000
	s_addc_u32 s39, s39, 0
	s_waitcnt lgkmcnt(2)
	global_store_dwordx4 v199, v[84:87], s[38:39]
	s_add_u32 s38, s38, 0x8000
	s_addc_u32 s39, s39, 0
	s_waitcnt lgkmcnt(1)
	global_store_dwordx4 v199, v[88:91], s[38:39]
	s_add_u32 s38, s38, 0x8000
	s_addc_u32 s39, s39, 0
	s_waitcnt lgkmcnt(0)
	global_store_dwordx4 v199, v[92:95], s[38:39]
